# attention phase without the per-segment s_setprio toggles (135 removed)
# baseline (speedup 1.0000x reference)
.LBB0_344:
	v_add_u32_e32 v0, v203, v207
	s_cmp_eq_u32 s83, s89
	v_cvt_f32_i32_e32 v172, v0
	s_cselect_b64 s[0:1], -1, 0
	s_cmp_eq_u32 s82, s89
	s_cselect_b64 s[40:41], -1, 0
	s_or_b64 s[40:41], s[0:1], s[40:41]
	s_mov_b64 s[0:1], -1
	s_andn2_b64 vcc, exec, s[40:41]
	v_add_f32_e32 v170, 0x41800000, v172
	v_add_f32_e32 v168, 0x42000000, v172
	v_add_f32_e32 v0, 0x42400000, v172
	s_cbranch_vccz .LBB0_346
	v_mov_b32_e32 v139, v169
	s_nop 0
	v_lshlrev_b32_e32 v66, 7, v139
	v_lshrrev_b32_e32 v138, 4, v139
	v_bfe_u32 v145, v139, 4, 2
	v_and_b32_e32 v66, 0x780, v66
	v_and_b32_e32 v173, 7, v139
	v_bitop3_b32 v67, v138, v173, 3 bitop3:0x6c
	v_add_u32_e32 v192, s88, v66
	v_bitop3_b32 v66, v145, v173, 4 bitop3:0x36
	v_lshl_add_u32 v86, v67, 4, v192
	v_lshl_add_u32 v94, v66, 4, v192
	ds_read_b128 v[66:69], v86
	ds_read_b128 v[70:73], v86 offset:2048
	ds_read_b128 v[74:77], v94
	ds_read_b128 v[78:81], v94 offset:2048
	ds_read_b128 v[82:85], v86 offset:4096
	ds_read_b128 v[86:89], v86 offset:6144
	ds_read_b128 v[90:93], v94 offset:4096
	ds_read_b128 v[94:97], v94 offset:6144
	v_lshlrev_b32_e32 v145, 2, v145
	v_or_b32_e32 v147, 1, v145
	v_cvt_f32_ubyte0_e32 v164, v145
	v_cvt_f32_ubyte0_e32 v165, v147
	v_or_b32_e32 v147, 3, v145
	v_or_b32_e32 v145, 2, v145
	v_cvt_f32_ubyte0_e32 v223, v147
	v_cvt_f32_ubyte0_e32 v222, v145
	v_pk_add_f32 v[226:227], v[172:173], v[164:165] op_sel_hi:[0,1]
	v_pk_add_f32 v[228:229], v[172:173], v[222:223] op_sel_hi:[0,1]
	v_mov_b32_e32 v147, v146
	v_pk_mul_f32 v[212:213], v[146:147], v[228:229]
	v_pk_mul_f32 v[210:211], v[156:157], v[226:227]
	s_waitcnt lgkmcnt(7)
	v_mfma_f32_16x16x32_bf16 v[210:213], v[66:69], v[2:5], v[210:213]
	s_waitcnt lgkmcnt(5)
	v_mfma_f32_16x16x32_bf16 v[210:213], v[74:77], v[6:9], v[210:213]
	v_pk_add_f32 v[230:231], v[170:171], v[164:165] op_sel_hi:[0,1]
	v_pk_add_f32 v[232:233], v[170:171], v[222:223] op_sel_hi:[0,1]
	v_pk_mul_f32 v[216:217], v[146:147], v[232:233]
	v_pk_mul_f32 v[214:215], v[156:157], v[230:231]
	s_nop 0
	v_mfma_f32_16x16x32_bf16 v[214:217], v[70:73], v[2:5], v[214:217]
	s_waitcnt lgkmcnt(4)
	v_mfma_f32_16x16x32_bf16 v[214:217], v[78:81], v[6:9], v[214:217]
	v_pk_add_f32 v[234:235], v[168:169], v[164:165] op_sel_hi:[0,1]
	v_pk_add_f32 v[236:237], v[168:169], v[222:223] op_sel_hi:[0,1]
	v_pk_mul_f32 v[220:221], v[146:147], v[236:237]
	v_pk_mul_f32 v[218:219], v[156:157], v[234:235]
	s_waitcnt lgkmcnt(3)
	v_mfma_f32_16x16x32_bf16 v[218:221], v[82:85], v[2:5], v[218:221]
	s_waitcnt lgkmcnt(1)
	v_mfma_f32_16x16x32_bf16 v[218:221], v[90:93], v[6:9], v[218:221]
	v_pk_add_f32 v[164:165], v[0:1], v[164:165] op_sel_hi:[0,1]
	v_pk_add_f32 v[238:239], v[0:1], v[222:223] op_sel_hi:[0,1]
	v_pk_mul_f32 v[224:225], v[146:147], v[238:239]
	v_pk_mul_f32 v[222:223], v[156:157], v[164:165]
	s_nop 0
	v_mfma_f32_16x16x32_bf16 v[222:225], v[86:89], v[2:5], v[222:225]
	s_waitcnt lgkmcnt(0)
	v_mfma_f32_16x16x32_bf16 v[222:225], v[94:97], v[6:9], v[222:225]
	v_exp_f32_e32 v241, v210
	v_exp_f32_e32 v243, v211
	v_exp_f32_e32 v245, v212
	v_exp_f32_e32 v247, v213
	v_exp_f32_e32 v249, v214
	v_exp_f32_e32 v251, v215
	v_exp_f32_e32 v179, v216
	v_exp_f32_e32 v181, v217
	v_exp_f32_e32 v187, v218
	v_exp_f32_e32 v189, v219
	v_exp_f32_e32 v175, v220
	v_exp_f32_e32 v177, v221
	v_exp_f32_e32 v197, v222
	v_exp_f32_e32 v223, v223
	v_exp_f32_e32 v191, v224
	v_exp_f32_e32 v225, v225
	v_mov_b32_e32 v145, v144
	v_cvt_pk_bf16_f32 v210, v241, v243
	v_cvt_pk_bf16_f32 v211, v245, v247
	v_cvt_pk_bf16_f32 v212, v249, v251
	v_cvt_pk_bf16_f32 v213, v179, v181
	v_cvt_pk_bf16_f32 v214, v187, v189
	v_cvt_pk_bf16_f32 v215, v175, v177
	v_cvt_pk_bf16_f32 v216, v197, v223
	v_cvt_pk_bf16_f32 v217, v191, v225
	v_pk_mul_f32 v[220:221], v[144:145], v[228:229]
	v_pk_mul_f32 v[218:219], v[158:159], v[226:227]
	s_nop 0
	v_mfma_f32_16x16x32_bf16 v[66:69], v[66:69], v[10:13], v[218:221]
	v_mfma_f32_16x16x32_bf16 v[66:69], v[74:77], v[14:17], v[66:69]
	v_pk_mul_f32 v[76:77], v[144:145], v[232:233]
	v_pk_mul_f32 v[74:75], v[158:159], v[230:231]
	s_nop 0
	v_mfma_f32_16x16x32_bf16 v[70:73], v[70:73], v[10:13], v[74:77]
	v_mfma_f32_16x16x32_bf16 v[70:73], v[78:81], v[14:17], v[70:73]
	s_nop 0
	v_pk_mul_f32 v[76:77], v[144:145], v[236:237]
	v_pk_mul_f32 v[74:75], v[158:159], v[234:235]
	s_nop 0
	v_mfma_f32_16x16x32_bf16 v[74:77], v[82:85], v[10:13], v[74:77]
	v_mfma_f32_16x16x32_bf16 v[74:77], v[90:93], v[14:17], v[74:77]
	v_pk_mul_f32 v[80:81], v[144:145], v[238:239]
	v_pk_mul_f32 v[78:79], v[158:159], v[164:165]
	s_nop 0
	v_mfma_f32_16x16x32_bf16 v[78:81], v[86:89], v[10:13], v[78:81]
	v_mfma_f32_16x16x32_bf16 v[78:81], v[94:97], v[14:17], v[78:81]
	v_exp_f32_e32 v240, v66
	v_exp_f32_e32 v242, v67
	v_exp_f32_e32 v244, v68
	v_exp_f32_e32 v246, v69
	v_pk_add_f32 v[66:67], v[240:241], 0 op_sel_hi:[1,0]
	v_exp_f32_e32 v248, v70
	v_pk_add_f32 v[66:67], v[242:243], v[66:67]
	v_exp_f32_e32 v250, v71
	v_pk_add_f32 v[66:67], v[244:245], v[66:67]
	v_exp_f32_e32 v178, v72
	v_exp_f32_e32 v180, v73
	v_pk_add_f32 v[66:67], v[246:247], v[66:67]
	v_exp_f32_e32 v186, v74
	v_pk_add_f32 v[66:67], v[66:67], v[248:249]
	v_exp_f32_e32 v188, v75
	v_pk_add_f32 v[66:67], v[250:251], v[66:67]
	v_lshrrev_b32_e32 v71, 1, v139
	v_exp_f32_e32 v174, v76
	v_pk_add_f32 v[66:67], v[178:179], v[66:67]
	v_bfe_u32 v70, v138, 1, 1
	v_and_b32_e32 v71, 8, v71
	v_exp_f32_e32 v176, v77
	v_pk_add_f32 v[66:67], v[180:181], v[66:67]
	v_add_u32_e32 v71, v192, v71
	v_bitop3_b32 v72, v70, v139, 7 bitop3:0x78
	v_exp_f32_e32 v196, v78
	v_pk_add_f32 v[66:67], v[66:67], v[186:187]
	v_lshl_add_u32 v138, v72, 4, v71
	v_bitop3_b32 v72, v70, v173, 2 bitop3:0x36
	v_exp_f32_e32 v222, v79
	v_pk_add_f32 v[66:67], v[188:189], v[66:67]
	v_lshl_add_u32 v139, v72, 4, v71
	v_bitop3_b32 v72, v70, v173, 4 bitop3:0x36
	v_bitop3_b32 v70, v70, v173, 6 bitop3:0x36
	v_pk_add_f32 v[66:67], v[174:175], v[66:67]
	v_exp_f32_e32 v190, v80
	v_lshl_add_u32 v145, v72, 4, v71
	v_lshl_add_u32 v147, v70, 4, v71
	ds_read_b64 v[70:71], v138 offset:8192
	ds_read_b64 v[72:73], v139 offset:8192
	ds_read_b64 v[74:75], v145 offset:8192
	ds_read_b64 v[76:77], v147 offset:8192
	v_pk_add_f32 v[66:67], v[176:177], v[66:67]
	v_exp_f32_e32 v224, v81
	v_pk_add_f32 v[66:67], v[66:67], v[196:197]
	v_cvt_pk_bf16_f32 v68, v248, v250
	v_pk_add_f32 v[66:67], v[222:223], v[66:67]
	v_cvt_pk_bf16_f32 v69, v178, v180
	v_pk_add_f32 v[66:67], v[190:191], v[66:67]
	v_cvt_pk_bf16_f32 v218, v186, v188
	v_pk_add_f32 v[66:67], v[224:225], v[66:67]
	v_cvt_pk_bf16_f32 v219, v174, v176
	v_pk_add_f32 v[164:165], v[166:167], v[66:67]
	v_cvt_pk_bf16_f32 v66, v240, v242
	v_cvt_pk_bf16_f32 v67, v244, v246
	v_cvt_pk_bf16_f32 v220, v196, v222
	v_cvt_pk_bf16_f32 v221, v190, v224
	s_waitcnt lgkmcnt(2)
	v_mfma_f32_16x16x32_bf16 v[78:81], v[70:73], v[210:213], v[110:113]
	v_mfma_f32_16x16x32_bf16 v[70:73], v[70:73], v[66:69], v[126:129]
	s_waitcnt lgkmcnt(0)
	v_mfma_f32_16x16x32_bf16 v[94:97], v[74:77], v[214:217], v[78:81]
	v_mfma_f32_16x16x32_bf16 v[78:81], v[74:77], v[218:221], v[70:73]
	s_nop 3
	ds_read_b64 v[70:71], v138 offset:10240
	ds_read_b64 v[72:73], v139 offset:10240
	ds_read_b64 v[74:75], v145 offset:10240
	ds_read_b64 v[76:77], v147 offset:10240
	s_waitcnt lgkmcnt(2)
	v_mfma_f32_16x16x32_bf16 v[82:85], v[70:73], v[210:213], v[106:109]
	v_mfma_f32_16x16x32_bf16 v[70:73], v[70:73], v[66:69], v[122:125]
	s_waitcnt lgkmcnt(0)
	v_mfma_f32_16x16x32_bf16 v[90:93], v[74:77], v[214:217], v[82:85]
	v_mfma_f32_16x16x32_bf16 v[74:77], v[74:77], v[218:221], v[70:73]
	s_nop 3
	ds_read_b64 v[70:71], v138 offset:12288
	ds_read_b64 v[72:73], v139 offset:12288
	ds_read_b64 v[82:83], v145 offset:12288
	ds_read_b64 v[84:85], v147 offset:12288
	s_waitcnt lgkmcnt(2)
	v_mfma_f32_16x16x32_bf16 v[86:89], v[70:73], v[210:213], v[102:105]
	v_mfma_f32_16x16x32_bf16 v[70:73], v[70:73], v[66:69], v[118:121]
	s_waitcnt lgkmcnt(0)
	v_mfma_f32_16x16x32_bf16 v[86:89], v[82:85], v[214:217], v[86:89]
	v_mfma_f32_16x16x32_bf16 v[70:73], v[82:85], v[218:221], v[70:73]
	ds_read_b64 v[222:223], v138 offset:14336
	ds_read_b64 v[224:225], v139 offset:14336
	ds_read_b64 v[226:227], v145 offset:14336
	ds_read_b64 v[228:229], v147 offset:14336
	s_waitcnt lgkmcnt(2)
	v_mfma_f32_16x16x32_bf16 v[82:85], v[222:225], v[210:213], v[98:101]
	v_mfma_f32_16x16x32_bf16 v[66:69], v[222:225], v[66:69], v[114:117]
	s_waitcnt lgkmcnt(0)
	v_mfma_f32_16x16x32_bf16 v[82:85], v[226:229], v[214:217], v[82:85]
	v_mfma_f32_16x16x32_bf16 v[66:69], v[226:229], v[218:221], v[66:69]
	s_mov_b64 s[0:1], 0
.LBB0_346:
	s_andn2_b64 vcc, exec, s[0:1]
	s_cbranch_vccnz .LBB0_348
	v_mov_b32_e32 v174, v169
	s_nop 2
	v_lshlrev_b32_e32 v66, 7, v174
	v_lshrrev_b32_e32 v175, 4, v174
	v_bfe_u32 v145, v174, 4, 2
	v_and_b32_e32 v66, 0x780, v66
	v_and_b32_e32 v176, 7, v174
	v_bitop3_b32 v67, v175, v176, 3 bitop3:0x6c
	v_add_u32_e32 v177, s88, v66
	v_bitop3_b32 v66, v145, v176, 4 bitop3:0x36
	v_lshl_add_u32 v86, v67, 4, v177
	v_lshl_add_u32 v94, v66, 4, v177
	ds_read_b128 v[66:69], v86
	ds_read_b128 v[70:73], v86 offset:2048
	ds_read_b128 v[74:77], v94
	ds_read_b128 v[78:81], v94 offset:2048
	ds_read_b128 v[82:85], v86 offset:4096
	ds_read_b128 v[86:89], v86 offset:6144
	ds_read_b128 v[90:93], v94 offset:4096
	ds_read_b128 v[94:97], v94 offset:6144
	v_lshlrev_b32_e32 v145, 2, v145
	v_or_b32_e32 v147, 1, v145
	v_cvt_f32_ubyte0_e32 v164, v145
	v_cvt_f32_ubyte0_e32 v165, v147
	v_or_b32_e32 v147, 3, v145
	v_or_b32_e32 v145, 2, v145
	v_pk_add_f32 v[226:227], v[172:173], v[164:165] op_sel_hi:[0,1]
	v_cvt_f32_ubyte0_e32 v223, v147
	v_cvt_f32_ubyte0_e32 v222, v145
	v_cmp_ge_f32_e32 vcc, 0, v226
	v_cmp_lt_f32_e64 s[0:1], s12, v226
	v_pk_add_f32 v[228:229], v[172:173], v[222:223] op_sel_hi:[0,1]
	v_mov_b32_e32 v147, v146
	s_and_b64 vcc, vcc, s[0:1]
	v_pk_mul_f32 v[212:213], v[146:147], v[228:229]
	v_pk_mul_f32 v[210:211], v[156:157], v[226:227]
	s_waitcnt lgkmcnt(7)
	v_mfma_f32_16x16x32_bf16 v[210:213], v[66:69], v[2:5], v[210:213]
	s_waitcnt lgkmcnt(5)
	v_mfma_f32_16x16x32_bf16 v[210:213], v[74:77], v[6:9], v[210:213]
	v_pk_add_f32 v[230:231], v[170:171], v[164:165] op_sel_hi:[0,1]
	v_pk_add_f32 v[232:233], v[170:171], v[222:223] op_sel_hi:[0,1]
	v_pk_mul_f32 v[216:217], v[146:147], v[232:233]
	v_pk_mul_f32 v[214:215], v[156:157], v[230:231]
	s_nop 0
	v_mfma_f32_16x16x32_bf16 v[214:217], v[70:73], v[2:5], v[214:217]
	s_waitcnt lgkmcnt(4)
	v_mfma_f32_16x16x32_bf16 v[214:217], v[78:81], v[6:9], v[214:217]
	v_pk_add_f32 v[234:235], v[168:169], v[164:165] op_sel_hi:[0,1]
	v_pk_add_f32 v[236:237], v[168:169], v[222:223] op_sel_hi:[0,1]
	v_pk_mul_f32 v[220:221], v[146:147], v[236:237]
	v_pk_mul_f32 v[218:219], v[156:157], v[234:235]
	s_waitcnt lgkmcnt(3)
	v_mfma_f32_16x16x32_bf16 v[218:221], v[82:85], v[2:5], v[218:221]
	s_waitcnt lgkmcnt(1)
	v_mfma_f32_16x16x32_bf16 v[218:221], v[90:93], v[6:9], v[218:221]
	v_pk_add_f32 v[164:165], v[0:1], v[164:165] op_sel_hi:[0,1]
	v_pk_add_f32 v[238:239], v[0:1], v[222:223] op_sel_hi:[0,1]
	v_pk_mul_f32 v[224:225], v[146:147], v[238:239]
	v_pk_mul_f32 v[222:223], v[156:157], v[164:165]
	s_nop 0
	v_mfma_f32_16x16x32_bf16 v[222:225], v[86:89], v[2:5], v[222:225]
	s_waitcnt lgkmcnt(0)
	v_mfma_f32_16x16x32_bf16 v[222:225], v[94:97], v[6:9], v[222:225]
	v_exp_f32_e32 v0, v210
	v_exp_f32_e32 v145, v211
	v_exp_f32_e32 v168, v212
	v_cmp_ge_f32_e64 s[0:1], 0, v227
	v_cmp_lt_f32_e64 s[40:41], s12, v227
	v_exp_f32_e32 v170, v213
	v_cndmask_b32_e32 v0, 0, v0, vcc
	s_and_b64 s[40:41], s[0:1], s[40:41]
	v_cmp_ge_f32_e64 s[0:1], 0, v228
	v_cmp_lt_f32_e64 s[42:43], s12, v228
	v_exp_f32_e32 v172, v214
	v_add_f32_e32 v147, 0, v0
	v_cndmask_b32_e64 v145, 0, v145, s[40:41]
	s_and_b64 s[42:43], s[0:1], s[42:43]
	v_cmp_ge_f32_e64 s[0:1], 0, v229
	v_cmp_lt_f32_e64 s[44:45], s12, v229
	v_exp_f32_e32 v178, v215
	v_add_f32_e32 v147, v145, v147
	v_cndmask_b32_e64 v168, 0, v168, s[42:43]
	s_and_b64 s[44:45], s[0:1], s[44:45]
	v_cmp_ge_f32_e64 s[0:1], 0, v230
	v_cmp_lt_f32_e64 s[46:47], s12, v230
	v_exp_f32_e32 v179, v216
	v_add_f32_e32 v147, v168, v147
	v_cndmask_b32_e64 v170, 0, v170, s[44:45]
	s_and_b64 s[46:47], s[0:1], s[46:47]
	v_cmp_ge_f32_e64 s[0:1], 0, v231
	v_cmp_lt_f32_e64 s[48:49], s12, v231
	v_exp_f32_e32 v180, v217
	v_add_f32_e32 v147, v170, v147
	v_cndmask_b32_e64 v172, 0, v172, s[46:47]
	s_and_b64 s[48:49], s[0:1], s[48:49]
	v_cmp_ge_f32_e64 s[0:1], 0, v232
	v_cmp_lt_f32_e64 s[50:51], s12, v232
	v_exp_f32_e32 v181, v218
	v_add_f32_e32 v147, v147, v172
	v_cndmask_b32_e64 v178, 0, v178, s[48:49]
	s_and_b64 s[50:51], s[0:1], s[50:51]
	v_cmp_ge_f32_e64 s[0:1], 0, v233
	v_cmp_lt_f32_e64 s[52:53], s12, v233
	v_exp_f32_e32 v186, v219
	v_add_f32_e32 v147, v178, v147
	v_cndmask_b32_e64 v179, 0, v179, s[50:51]
	s_and_b64 s[52:53], s[0:1], s[52:53]
	v_cmp_ge_f32_e64 s[0:1], 0, v234
	v_cmp_lt_f32_e64 s[54:55], s12, v234
	v_exp_f32_e32 v187, v220
	v_add_f32_e32 v147, v179, v147
	v_cndmask_b32_e64 v180, 0, v180, s[52:53]
	s_and_b64 s[54:55], s[0:1], s[54:55]
	v_cmp_ge_f32_e64 s[0:1], 0, v235
	v_cmp_lt_f32_e64 s[56:57], s12, v235
	v_exp_f32_e32 v188, v221
	v_add_f32_e32 v147, v180, v147
	v_cndmask_b32_e64 v181, 0, v181, s[54:55]
	s_and_b64 s[56:57], s[0:1], s[56:57]
	v_cmp_ge_f32_e64 s[0:1], 0, v236
	v_cmp_lt_f32_e64 s[58:59], s12, v236
	v_exp_f32_e32 v189, v222
	v_add_f32_e32 v147, v147, v181
	v_cndmask_b32_e64 v186, 0, v186, s[56:57]
	s_and_b64 s[58:59], s[0:1], s[58:59]
	v_cmp_ge_f32_e64 s[0:1], 0, v237
	v_cmp_lt_f32_e64 s[60:61], s12, v237
	v_exp_f32_e32 v190, v223
	v_add_f32_e32 v147, v186, v147
	v_cndmask_b32_e64 v187, 0, v187, s[58:59]
	s_and_b64 s[60:61], s[0:1], s[60:61]
	v_cmp_ge_f32_e64 s[0:1], 0, v164
	v_cmp_lt_f32_e64 s[62:63], s12, v164
	v_add_f32_e32 v147, v187, v147
	v_cndmask_b32_e64 v188, 0, v188, s[60:61]
	s_and_b64 s[62:63], s[0:1], s[62:63]
	v_cmp_ge_f32_e64 s[0:1], 0, v165
	v_cmp_lt_f32_e64 s[64:65], s12, v165
	v_add_f32_e32 v147, v188, v147
	v_cndmask_b32_e64 v189, 0, v189, s[62:63]
	s_and_b64 s[64:65], s[0:1], s[64:65]
	v_add_f32_e32 v147, v147, v189
	v_cndmask_b32_e64 v190, 0, v190, s[64:65]
	v_add_f32_e32 v223, v190, v147
	v_exp_f32_e32 v147, v224
	v_cmp_ge_f32_e64 s[0:1], 0, v238
	v_cmp_lt_f32_e64 s[66:67], s12, v238
	s_and_b64 s[68:69], s[0:1], s[66:67]
	v_cmp_ge_f32_e64 s[0:1], 0, v239
	v_cmp_lt_f32_e64 s[66:67], s12, v239
	s_and_b64 s[66:67], s[0:1], s[66:67]
	v_cvt_pk_bf16_f32 v210, v0, v145
	v_mov_b32_e32 v145, v144
	v_cndmask_b32_e64 v241, 0, v147, s[68:69]
	v_exp_f32_e32 v147, v225
	v_cvt_pk_bf16_f32 v211, v168, v170
	v_cvt_pk_bf16_f32 v212, v172, v178
	v_cvt_pk_bf16_f32 v213, v179, v180
	v_cvt_pk_bf16_f32 v214, v181, v186
	v_cvt_pk_bf16_f32 v215, v187, v188
	v_cvt_pk_bf16_f32 v216, v189, v190
	v_pk_mul_f32 v[220:221], v[144:145], v[228:229]
	v_pk_mul_f32 v[218:219], v[158:159], v[226:227]
	s_nop 0
	v_mfma_f32_16x16x32_bf16 v[66:69], v[66:69], v[10:13], v[218:221]
	v_mfma_f32_16x16x32_bf16 v[66:69], v[74:77], v[14:17], v[66:69]
	v_pk_mul_f32 v[76:77], v[144:145], v[232:233]
	v_pk_mul_f32 v[74:75], v[158:159], v[230:231]
	s_nop 0
	v_mfma_f32_16x16x32_bf16 v[70:73], v[70:73], v[10:13], v[74:77]
	v_mfma_f32_16x16x32_bf16 v[70:73], v[78:81], v[14:17], v[70:73]
	s_nop 0
	v_pk_mul_f32 v[76:77], v[144:145], v[236:237]
	v_pk_mul_f32 v[74:75], v[158:159], v[234:235]
	s_nop 0
	v_mfma_f32_16x16x32_bf16 v[74:77], v[82:85], v[10:13], v[74:77]
	v_mfma_f32_16x16x32_bf16 v[74:77], v[90:93], v[14:17], v[74:77]
	v_pk_mul_f32 v[80:81], v[144:145], v[238:239]
	v_pk_mul_f32 v[78:79], v[158:159], v[164:165]
	s_nop 0
	v_mfma_f32_16x16x32_bf16 v[78:81], v[86:89], v[10:13], v[78:81]
	v_mfma_f32_16x16x32_bf16 v[78:81], v[94:97], v[14:17], v[78:81]
	v_exp_f32_e32 v0, v66
	v_exp_f32_e32 v66, v67
	v_exp_f32_e32 v67, v68
	v_exp_f32_e32 v69, v69
	v_cndmask_b32_e32 v0, 0, v0, vcc
	v_cndmask_b32_e64 v68, 0, v66, s[40:41]
	v_cndmask_b32_e64 v82, 0, v67, s[42:43]
	v_exp_f32_e32 v67, v70
	v_exp_f32_e32 v70, v71
	v_add_f32_e32 v66, 0, v0
	v_add_f32_e32 v66, v68, v66
	v_cndmask_b32_e64 v71, 0, v67, s[46:47]
	v_exp_f32_e32 v67, v72
	v_exp_f32_e32 v72, v73
	v_add_f32_e32 v66, v82, v66
	v_cndmask_b32_e64 v69, 0, v69, s[44:45]
	v_cndmask_b32_e64 v73, 0, v67, s[50:51]
	v_exp_f32_e32 v67, v74
	v_exp_f32_e32 v74, v75
	v_add_f32_e32 v66, v69, v66
	v_add_f32_e32 v66, v66, v71
	v_cndmask_b32_e64 v83, 0, v67, s[54:55]
	v_exp_f32_e32 v67, v76
	v_cndmask_b32_e64 v84, 0, v74, s[56:57]
	v_exp_f32_e32 v74, v77
	v_cndmask_b32_e64 v70, 0, v70, s[48:49]
	v_add_f32_e32 v66, v70, v66
	v_cndmask_b32_e64 v85, 0, v67, s[58:59]
	v_exp_f32_e32 v67, v78
	v_add_f32_e32 v66, v73, v66
	v_cndmask_b32_e64 v72, 0, v72, s[52:53]
	v_cndmask_b32_e64 v86, 0, v74, s[60:61]
	v_exp_f32_e32 v74, v79
	v_add_f32_e32 v66, v72, v66
	v_add_f32_e32 v66, v66, v83
	v_add_f32_e32 v66, v84, v66
	v_cndmask_b32_e64 v87, 0, v67, s[62:63]
	v_exp_f32_e32 v67, v80
	v_add_f32_e32 v66, v85, v66
	v_cndmask_b32_e64 v80, 0, v74, s[64:65]
	v_exp_f32_e32 v74, v81
	v_add_f32_e32 v66, v86, v66
	v_add_f32_e32 v66, v66, v87
	v_add_f32_e32 v222, v80, v66
	v_cndmask_b32_e64 v240, 0, v67, s[68:69]
	v_pk_add_f32 v[66:67], v[240:241], v[222:223]
	v_cndmask_b32_e64 v79, 0, v147, s[66:67]
	v_cndmask_b32_e64 v78, 0, v74, s[66:67]
	v_pk_add_f32 v[66:67], v[78:79], v[66:67]
	s_mov_b32 s65, s91
	v_pk_add_f32 v[164:165], v[166:167], v[66:67]
	v_cvt_pk_bf16_f32 v66, v0, v68
	v_cvt_pk_bf16_f32 v68, v71, v70
	v_lshrrev_b32_e32 v70, 1, v174
	v_bfe_u32 v0, v175, 1, 1
	v_and_b32_e32 v70, 8, v70
	v_add_u32_e32 v70, v177, v70
	v_bitop3_b32 v71, v0, v174, 7 bitop3:0x78
	v_lshl_add_u32 v145, v71, 4, v70
	v_bitop3_b32 v71, v0, v176, 2 bitop3:0x36
	v_lshl_add_u32 v147, v71, 4, v70
	v_bitop3_b32 v71, v0, v176, 4 bitop3:0x36
	v_bitop3_b32 v0, v0, v176, 6 bitop3:0x36
	v_cvt_pk_bf16_f32 v67, v82, v69
	v_cvt_pk_bf16_f32 v69, v73, v72
	v_lshl_add_u32 v166, v71, 4, v70
	v_lshl_add_u32 v0, v0, 4, v70
	ds_read_b64 v[70:71], v145 offset:8192
	ds_read_b64 v[72:73], v147 offset:8192
	ds_read_b64 v[74:75], v166 offset:8192
	ds_read_b64 v[76:77], v0 offset:8192
	s_movk_i32 s64, 0x1ff0
	s_mov_b64 s[68:69], 0x800
	s_mov_b32 s67, 0x3f80000
	s_mov_b32 s66, 0x14991000
	v_cvt_pk_bf16_f32 v217, v241, v79
	v_cvt_pk_bf16_f32 v218, v83, v84
	v_cvt_pk_bf16_f32 v219, v85, v86
	v_cvt_pk_bf16_f32 v220, v87, v80
	v_cvt_pk_bf16_f32 v221, v240, v78
	s_waitcnt lgkmcnt(2)
	v_mfma_f32_16x16x32_bf16 v[78:81], v[70:73], v[210:213], v[110:113]
	v_mfma_f32_16x16x32_bf16 v[70:73], v[70:73], v[66:69], v[126:129]
	s_waitcnt lgkmcnt(0)
	v_mfma_f32_16x16x32_bf16 v[94:97], v[74:77], v[214:217], v[78:81]
	v_mfma_f32_16x16x32_bf16 v[78:81], v[74:77], v[218:221], v[70:73]
	s_nop 3
	ds_read_b64 v[70:71], v145 offset:10240
	ds_read_b64 v[72:73], v147 offset:10240
	ds_read_b64 v[74:75], v166 offset:10240
	ds_read_b64 v[76:77], v0 offset:10240
	s_waitcnt lgkmcnt(2)
	v_mfma_f32_16x16x32_bf16 v[82:85], v[70:73], v[210:213], v[106:109]
	v_mfma_f32_16x16x32_bf16 v[70:73], v[70:73], v[66:69], v[122:125]
	s_waitcnt lgkmcnt(0)
	v_mfma_f32_16x16x32_bf16 v[90:93], v[74:77], v[214:217], v[82:85]
	v_mfma_f32_16x16x32_bf16 v[74:77], v[74:77], v[218:221], v[70:73]
	s_nop 3
	ds_read_b64 v[70:71], v145 offset:12288
	ds_read_b64 v[72:73], v147 offset:12288
	ds_read_b64 v[82:83], v166 offset:12288
	ds_read_b64 v[84:85], v0 offset:12288
	s_waitcnt lgkmcnt(2)
	v_mfma_f32_16x16x32_bf16 v[86:89], v[70:73], v[210:213], v[102:105]
	v_mfma_f32_16x16x32_bf16 v[70:73], v[70:73], v[66:69], v[118:121]
	s_waitcnt lgkmcnt(0)
	v_mfma_f32_16x16x32_bf16 v[86:89], v[82:85], v[214:217], v[86:89]
	v_mfma_f32_16x16x32_bf16 v[70:73], v[82:85], v[218:221], v[70:73]
	ds_read_b64 v[102:103], v145 offset:14336
	ds_read_b64 v[104:105], v147 offset:14336
	ds_read_b64 v[106:107], v166 offset:14336
	ds_read_b64 v[108:109], v0 offset:14336
	s_waitcnt lgkmcnt(2)
	v_mfma_f32_16x16x32_bf16 v[82:85], v[102:105], v[210:213], v[98:101]
	v_mfma_f32_16x16x32_bf16 v[66:69], v[102:105], v[66:69], v[114:117]
	s_waitcnt lgkmcnt(0)
	v_mfma_f32_16x16x32_bf16 v[82:85], v[106:109], v[214:217], v[82:85]
	v_mfma_f32_16x16x32_bf16 v[66:69], v[106:109], v[218:221], v[66:69]

.LBB0_352:
	v_mov_b32_e32 v102, v169
	v_add_u32_e32 v0, v198, v204
	v_lshlrev_b32_e32 v66, 7, v102
	v_lshrrev_b32_e32 v75, 4, v102
	v_and_b32_e32 v66, 0x780, v66
	v_and_b32_e32 v74, 7, v102
	v_bfe_u32 v101, v102, 4, 2
	v_bitop3_b32 v67, v75, v74, 3 bitop3:0x6c
	v_add_u32_e32 v76, s88, v66
	v_lshl_add_u32 v66, v67, 4, v76
	v_bitop3_b32 v67, v101, v74, 4 bitop3:0x36
	v_lshl_add_u32 v67, v67, 4, v76
	ds_read_b128 v[70:73], v66
	ds_read_b128 v[78:81], v66 offset:2048
	ds_read_b128 v[86:89], v67
	ds_read_b128 v[90:93], v67 offset:2048
	ds_read_b128 v[94:97], v66 offset:4096
	ds_read_b128 v[118:121], v66 offset:6144
	ds_read_b128 v[122:125], v67 offset:4096
	ds_read_b128 v[126:129], v67 offset:6144
	v_cvt_f32_i32_e32 v0, v0
	v_lshlrev_b32_e32 v66, 6, v101
	v_or_b32_e32 v67, 16, v66
	v_cvt_f32_ubyte0_e32 v108, v66
	v_cvt_f32_ubyte0_e32 v109, v67
	v_or_b32_e32 v67, 48, v66
	v_or_b32_e32 v66, 32, v66
	v_cvt_f32_ubyte0_e32 v111, v67
	v_cvt_f32_ubyte0_e32 v110, v66
	v_pk_add_f32 v[166:167], v[0:1], v[108:109] op_sel_hi:[0,1]
	v_pk_add_f32 v[214:215], v[0:1], v[110:111] op_sel_hi:[0,1]
	v_mov_b32_e32 v147, v146
	v_pk_mul_f32 v[68:69], v[146:147], v[214:215]
	v_pk_mul_f32 v[66:67], v[156:157], v[166:167]
	s_waitcnt lgkmcnt(7)
	v_mfma_f32_16x16x32_bf16 v[66:69], v[70:73], v[2:5], v[66:69]
	s_waitcnt lgkmcnt(5)
	v_mfma_f32_16x16x32_bf16 v[66:69], v[86:89], v[6:9], v[66:69]
	v_add_f32_e32 v82, 0x43800000, v0
	v_pk_add_f32 v[216:217], v[82:83], v[108:109] op_sel_hi:[0,1]
	v_pk_add_f32 v[218:219], v[82:83], v[110:111] op_sel_hi:[0,1]
	v_pk_mul_f32 v[84:85], v[146:147], v[218:219]
	v_pk_mul_f32 v[82:83], v[156:157], v[216:217]
	s_nop 0
	v_mfma_f32_16x16x32_bf16 v[82:85], v[78:81], v[2:5], v[82:85]
	s_waitcnt lgkmcnt(4)
	v_mfma_f32_16x16x32_bf16 v[82:85], v[90:93], v[6:9], v[82:85]
	v_add_f32_e32 v104, 0x44000000, v0
	v_pk_add_f32 v[220:221], v[104:105], v[108:109] op_sel_hi:[0,1]
	v_pk_add_f32 v[222:223], v[104:105], v[110:111] op_sel_hi:[0,1]
	v_pk_mul_f32 v[106:107], v[146:147], v[222:223]
	v_pk_mul_f32 v[104:105], v[156:157], v[220:221]
	s_waitcnt lgkmcnt(3)
	v_mfma_f32_16x16x32_bf16 v[104:107], v[94:97], v[2:5], v[104:107]
	s_waitcnt lgkmcnt(1)
	v_mfma_f32_16x16x32_bf16 v[112:115], v[122:125], v[6:9], v[104:107]
	v_add_f32_e32 v0, 0x44400000, v0
	v_pk_add_f32 v[224:225], v[0:1], v[108:109] op_sel_hi:[0,1]
	v_pk_add_f32 v[226:227], v[0:1], v[110:111] op_sel_hi:[0,1]
	s_nop 1
	v_pk_mul_f32 v[106:107], v[146:147], v[226:227]
	v_pk_mul_f32 v[104:105], v[156:157], v[224:225]
	s_nop 0
	v_mfma_f32_16x16x32_bf16 v[104:107], v[118:121], v[2:5], v[104:107]
	s_waitcnt lgkmcnt(0)
	v_mfma_f32_16x16x32_bf16 v[210:213], v[126:129], v[6:9], v[104:107]
	v_exp_f32_e32 v0, v66
	v_cmp_ge_f32_e32 vcc, 0, v166
	v_cmp_lt_f32_e64 s[0:1], s13, v166
	s_and_b64 s[68:69], vcc, s[0:1]
	v_cndmask_b32_e64 v0, 0, v0, s[68:69]
	v_mul_f32_e32 v66, v99, v0
	v_fma_f32 v103, v99, v0, 0
	v_exp_f32_e32 v0, v67
	v_cmp_ge_f32_e32 vcc, 0, v167
	v_cmp_lt_f32_e64 s[0:1], s13, v167
	s_and_b64 s[66:67], vcc, s[0:1]
	v_cndmask_b32_e64 v0, 0, v0, s[66:67]
	v_mul_f32_e32 v67, v99, v0
	v_fma_f32 v104, v99, v0, 0
	v_exp_f32_e32 v0, v68
	v_cmp_ge_f32_e32 vcc, 0, v214
	v_cmp_lt_f32_e64 s[0:1], s13, v214
	s_and_b64 s[64:65], vcc, s[0:1]
	v_cndmask_b32_e64 v0, 0, v0, s[64:65]
	v_mul_f32_e32 v68, v99, v0
	v_fma_f32 v105, v99, v0, 0
	v_exp_f32_e32 v0, v69
	v_cmp_ge_f32_e32 vcc, 0, v215
	v_cmp_lt_f32_e64 s[0:1], s13, v215
	s_and_b64 s[62:63], vcc, s[0:1]
	v_cndmask_b32_e64 v0, 0, v0, s[62:63]
	v_mul_f32_e32 v69, v99, v0
	v_fma_f32 v106, v99, v0, 0
	v_exp_f32_e32 v0, v82
	v_cmp_ge_f32_e32 vcc, 0, v216
	v_cmp_lt_f32_e64 s[0:1], s13, v216
	s_and_b64 s[60:61], vcc, s[0:1]
	v_cndmask_b32_e64 v0, 0, v0, s[60:61]
	v_mul_f32_e32 v77, v99, v0
	v_fma_f32 v107, v99, v0, 0
	v_exp_f32_e32 v0, v83
	v_cmp_ge_f32_e32 vcc, 0, v217
	v_cmp_lt_f32_e64 s[0:1], s13, v217
	s_and_b64 s[58:59], vcc, s[0:1]
	v_cndmask_b32_e64 v0, 0, v0, s[58:59]
	v_mul_f32_e32 v82, v99, v0
	v_fma_f32 v108, v99, v0, 0
	v_exp_f32_e32 v0, v84
	v_cmp_ge_f32_e32 vcc, 0, v218
	v_cmp_lt_f32_e64 s[0:1], s13, v218
	s_and_b64 s[56:57], vcc, s[0:1]
	v_cndmask_b32_e64 v0, 0, v0, s[56:57]
	v_mul_f32_e32 v83, v99, v0
	v_fma_f32 v109, v99, v0, 0
	v_exp_f32_e32 v0, v85
	v_cmp_ge_f32_e32 vcc, 0, v219
	v_cmp_lt_f32_e64 s[0:1], s13, v219
	s_and_b64 s[54:55], vcc, s[0:1]
	v_cndmask_b32_e64 v0, 0, v0, s[54:55]
	v_mul_f32_e32 v84, v99, v0
	v_fma_f32 v110, v99, v0, 0
	v_exp_f32_e32 v0, v112
	v_cmp_ge_f32_e32 vcc, 0, v220
	v_cmp_lt_f32_e64 s[0:1], s13, v220
	s_and_b64 s[52:53], vcc, s[0:1]
	v_cndmask_b32_e64 v0, 0, v0, s[52:53]
	v_mul_f32_e32 v85, v99, v0
	v_fma_f32 v111, v99, v0, 0
	v_exp_f32_e32 v0, v113
	v_cmp_ge_f32_e32 vcc, 0, v221
	v_cmp_lt_f32_e64 s[0:1], s13, v221
	s_and_b64 s[50:51], vcc, s[0:1]
	v_cndmask_b32_e64 v0, 0, v0, s[50:51]
	v_mul_f32_e32 v145, v99, v0
	v_fma_f32 v112, v99, v0, 0
	v_exp_f32_e32 v0, v114
	v_cmp_ge_f32_e32 vcc, 0, v222
	v_cmp_lt_f32_e64 s[0:1], s13, v222
	s_and_b64 s[48:49], vcc, s[0:1]
	v_cndmask_b32_e64 v0, 0, v0, s[48:49]
	v_mul_f32_e32 v147, v99, v0
	v_fma_f32 v113, v99, v0, 0
	v_exp_f32_e32 v0, v115
	v_cmp_ge_f32_e32 vcc, 0, v223
	v_cmp_lt_f32_e64 s[0:1], s13, v223
	s_and_b64 s[46:47], vcc, s[0:1]
	v_cndmask_b32_e64 v0, 0, v0, s[46:47]
	v_mul_f32_e32 v168, v99, v0
	v_fma_f32 v114, v99, v0, 0
	v_exp_f32_e32 v0, v210
	v_cmp_ge_f32_e32 vcc, 0, v224
	v_cmp_lt_f32_e64 s[0:1], s13, v224
	s_and_b64 s[44:45], vcc, s[0:1]
	v_cndmask_b32_e64 v0, 0, v0, s[44:45]
	v_mul_f32_e32 v170, v99, v0
	v_fma_f32 v115, v99, v0, 0
	v_exp_f32_e32 v0, v211
	v_cmp_ge_f32_e32 vcc, 0, v225
	v_cmp_lt_f32_e64 s[0:1], s13, v225
	s_and_b64 s[42:43], vcc, s[0:1]
	v_cndmask_b32_e64 v0, 0, v0, s[42:43]
	v_mul_f32_e32 v172, v99, v0
	v_fma_f32 v116, v99, v0, 0
	v_exp_f32_e32 v0, v212
	v_cmp_ge_f32_e32 vcc, 0, v226
	v_cmp_lt_f32_e64 s[0:1], s13, v226
	s_and_b64 s[40:41], vcc, s[0:1]
	v_cndmask_b32_e64 v0, 0, v0, s[40:41]
	v_mul_f32_e32 v174, v99, v0
	v_fma_f32 v117, v99, v0, 0
	v_exp_f32_e32 v0, v213
	v_cmp_ge_f32_e32 vcc, 0, v227
	v_cmp_lt_f32_e64 s[0:1], s13, v227
	s_and_b64 vcc, vcc, s[0:1]
	v_cndmask_b32_e32 v0, 0, v0, vcc
	v_mul_f32_e32 v175, v99, v0
	v_fma_f32 v0, v99, v0, 0
	v_cvt_pk_bf16_f32 v66, v66, v67
	v_cvt_pk_bf16_f32 v67, v68, v69
	v_cvt_pk_bf16_f32 v68, v77, v82
	v_cvt_pk_bf16_f32 v69, v83, v84
	v_cvt_pk_bf16_f32 v82, v85, v145
	v_cvt_pk_bf16_f32 v83, v147, v168
	v_cvt_pk_bf16_f32 v84, v170, v172
	v_cvt_pk_bf16_f32 v85, v174, v175
	v_mov_b32_e32 v145, v144
	v_pk_mul_f32 v[212:213], v[144:145], v[214:215]
	v_pk_mul_f32 v[210:211], v[158:159], v[166:167]
	s_nop 0
	v_mfma_f32_16x16x32_bf16 v[70:73], v[70:73], v[10:13], v[210:213]
	v_mfma_f32_16x16x32_bf16 v[86:89], v[86:89], v[14:17], v[70:73]
	s_nop 5
	v_pk_mul_f32 v[72:73], v[144:145], v[218:219]
	v_pk_mul_f32 v[70:71], v[158:159], v[216:217]
	s_nop 0
	v_mfma_f32_16x16x32_bf16 v[70:73], v[78:81], v[10:13], v[70:73]
	v_mfma_f32_16x16x32_bf16 v[78:81], v[90:93], v[14:17], v[70:73]
	s_nop 5
	v_pk_mul_f32 v[72:73], v[144:145], v[222:223]
	v_pk_mul_f32 v[70:71], v[158:159], v[220:221]
	s_nop 0
	v_mfma_f32_16x16x32_bf16 v[70:73], v[94:97], v[10:13], v[70:73]
	v_mfma_f32_16x16x32_bf16 v[90:93], v[122:125], v[14:17], v[70:73]
	s_nop 5
	v_pk_mul_f32 v[72:73], v[144:145], v[226:227]
	v_pk_mul_f32 v[70:71], v[158:159], v[224:225]
	s_nop 0
	v_mfma_f32_16x16x32_bf16 v[70:73], v[118:121], v[10:13], v[70:73]
	v_mfma_f32_16x16x32_bf16 v[70:73], v[126:129], v[14:17], v[70:73]
	v_exp_f32_e32 v77, v86
	s_nop 5
	v_exp_f32_e32 v70, v70
	v_bfe_u32 v75, v75, 1, 1
	v_cndmask_b32_e64 v77, 0, v77, s[68:69]
	v_mul_f32_e32 v86, v98, v77
	v_fmac_f32_e32 v103, v98, v77
	v_exp_f32_e32 v77, v87
	v_cndmask_b32_e64 v70, 0, v70, s[44:45]
	v_fmac_f32_e32 v115, v98, v70
	v_cndmask_b32_e64 v77, 0, v77, s[66:67]
	v_mul_f32_e32 v87, v98, v77
	v_fmac_f32_e32 v104, v98, v77
	v_exp_f32_e32 v77, v88
	v_cvt_pk_bf16_f32 v118, v86, v87
	v_cndmask_b32_e64 v77, 0, v77, s[64:65]
	v_mul_f32_e32 v88, v98, v77
	v_fmac_f32_e32 v105, v98, v77
	v_exp_f32_e32 v77, v89
	s_nop 0
	v_cndmask_b32_e64 v77, 0, v77, s[62:63]
	v_mul_f32_e32 v89, v98, v77
	v_fmac_f32_e32 v106, v98, v77
	v_exp_f32_e32 v77, v78
	v_cvt_pk_bf16_f32 v119, v88, v89
	v_cndmask_b32_e64 v77, 0, v77, s[60:61]
	v_mul_f32_e32 v78, v98, v77
	v_fmac_f32_e32 v107, v98, v77
	v_exp_f32_e32 v77, v79
	s_nop 0
	v_cndmask_b32_e64 v77, 0, v77, s[58:59]
	v_mul_f32_e32 v79, v98, v77
	v_fmac_f32_e32 v108, v98, v77
	v_exp_f32_e32 v77, v80
	v_cvt_pk_bf16_f32 v120, v78, v79
	v_cndmask_b32_e64 v77, 0, v77, s[56:57]
	v_mul_f32_e32 v80, v98, v77
	v_fmac_f32_e32 v109, v98, v77
	v_exp_f32_e32 v77, v81
	s_nop 0
	v_cndmask_b32_e64 v77, 0, v77, s[54:55]
	v_mul_f32_e32 v81, v98, v77
	v_fmac_f32_e32 v110, v98, v77
	v_exp_f32_e32 v77, v90
	v_cvt_pk_bf16_f32 v121, v80, v81
	v_cndmask_b32_e64 v77, 0, v77, s[52:53]
	v_mul_f32_e32 v90, v98, v77
	v_fmac_f32_e32 v111, v98, v77
	v_exp_f32_e32 v77, v91
	s_nop 0
	v_cndmask_b32_e64 v77, 0, v77, s[50:51]
	v_mul_f32_e32 v91, v98, v77
	v_fmac_f32_e32 v112, v98, v77
	v_exp_f32_e32 v77, v92
	v_cvt_pk_bf16_f32 v122, v90, v91
	v_cndmask_b32_e64 v77, 0, v77, s[48:49]
	v_mul_f32_e32 v92, v98, v77
	v_fmac_f32_e32 v113, v98, v77
	v_exp_f32_e32 v77, v93
	s_nop 0
	v_cndmask_b32_e64 v77, 0, v77, s[46:47]
	v_mul_f32_e32 v93, v98, v77
	v_fmac_f32_e32 v114, v98, v77
	v_mul_f32_e32 v77, v98, v70
	v_exp_f32_e32 v70, v71
	v_cvt_pk_bf16_f32 v123, v92, v93
	v_cndmask_b32_e64 v70, 0, v70, s[42:43]
	v_mul_f32_e32 v71, v98, v70
	v_fmac_f32_e32 v116, v98, v70
	v_exp_f32_e32 v70, v72
	v_cvt_pk_bf16_f32 v124, v77, v71
	v_cndmask_b32_e64 v70, 0, v70, s[40:41]
	v_mul_f32_e32 v72, v98, v70
	v_fmac_f32_e32 v117, v98, v70
	v_exp_f32_e32 v70, v73
	s_nop 0
	v_cndmask_b32_e32 v70, 0, v70, vcc
	v_mul_f32_e32 v73, v98, v70
	v_fmac_f32_e32 v0, v98, v70
	v_lshrrev_b32_e32 v70, 1, v102
	v_and_b32_e32 v70, 8, v70
	v_cvt_pk_bf16_f32 v125, v72, v73
	v_add_u32_e32 v78, v76, v70
	v_bitop3_b32 v70, v75, v102, 7 bitop3:0x78
	v_bitop3_b32 v72, v75, v74, 2 bitop3:0x36
	v_bitop3_b32 v76, v75, v74, 4 bitop3:0x36
	v_bitop3_b32 v74, v75, v74, 6 bitop3:0x36
	v_lshl_add_u32 v145, v70, 4, v78
	v_lshl_add_u32 v147, v72, 4, v78
	v_lshl_add_u32 v166, v76, 4, v78
	v_lshl_add_u32 v167, v74, 4, v78
	ds_read_b64 v[70:71], v145 offset:8192
	ds_read_b64 v[72:73], v147 offset:8192
	ds_read_b64 v[76:77], v166 offset:8192
	ds_read_b64 v[78:79], v167 offset:8192
	s_waitcnt lgkmcnt(2)
	v_mfma_f32_16x16x32_bf16 v[86:89], v[70:73], v[66:69], v[62:65]
	v_mfma_f32_16x16x32_bf16 v[70:73], v[70:73], v[118:121], v[46:49]
	s_waitcnt lgkmcnt(0)
	v_mfma_f32_16x16x32_bf16 v[94:97], v[76:79], v[82:85], v[86:89]
	v_mfma_f32_16x16x32_bf16 v[78:81], v[76:79], v[122:125], v[70:73]
	s_nop 3
	ds_read_b64 v[70:71], v145 offset:10240
	ds_read_b64 v[72:73], v147 offset:10240
	ds_read_b64 v[74:75], v166 offset:10240
	ds_read_b64 v[76:77], v167 offset:10240
	s_waitcnt lgkmcnt(2)
	v_mfma_f32_16x16x32_bf16 v[86:89], v[70:73], v[66:69], v[58:61]
	v_mfma_f32_16x16x32_bf16 v[70:73], v[70:73], v[118:121], v[42:45]
	s_waitcnt lgkmcnt(0)
	v_mfma_f32_16x16x32_bf16 v[90:93], v[74:77], v[82:85], v[86:89]
	v_mfma_f32_16x16x32_bf16 v[74:77], v[74:77], v[122:125], v[70:73]
	s_nop 3
	ds_read_b64 v[70:71], v145 offset:12288
	ds_read_b64 v[72:73], v147 offset:12288
	ds_read_b64 v[126:127], v166 offset:12288
	ds_read_b64 v[128:129], v167 offset:12288
	s_waitcnt lgkmcnt(2)
	v_mfma_f32_16x16x32_bf16 v[86:89], v[70:73], v[66:69], v[54:57]
	v_mfma_f32_16x16x32_bf16 v[70:73], v[70:73], v[118:121], v[38:41]
	s_waitcnt lgkmcnt(0)
	v_mfma_f32_16x16x32_bf16 v[86:89], v[126:129], v[82:85], v[86:89]
	v_mfma_f32_16x16x32_bf16 v[70:73], v[126:129], v[122:125], v[70:73]
	ds_read_b64 v[126:127], v145 offset:14336
	ds_read_b64 v[128:129], v147 offset:14336
	ds_read_b64 v[210:211], v166 offset:14336
	ds_read_b64 v[212:213], v167 offset:14336
	s_waitcnt lgkmcnt(2)
	v_mfma_f32_16x16x32_bf16 v[66:69], v[126:129], v[66:69], v[50:53]
	s_waitcnt lgkmcnt(0)
	v_mfma_f32_16x16x32_bf16 v[82:85], v[210:213], v[82:85], v[66:69]
	v_mfma_f32_16x16x32_bf16 v[66:69], v[126:129], v[118:121], v[34:37]
	v_mfma_f32_16x16x32_bf16 v[66:69], v[210:213], v[122:125], v[66:69]
	v_add_u32_e32 v102, 48, v102
	v_and_b32_e32 v102, 63, v102
	v_and_or_b32 v102, v182, 64, v102
	v_cmp_eq_u32_e32 vcc, 3, v101
	v_lshlrev_b32_e32 v118, 2, v102
	v_lshlrev_b32_e32 v102, 2, v101
	v_cndmask_b32_e32 v100, v106, v100, vcc
	v_add3_u32 v119, s81, v102, v206
	ds_bpermute_b32 v102, v118, v100
	v_add_f32_e32 v100, v103, v104
	v_add_f32_e32 v100, v105, v100
	v_add_f32_e32 v103, v106, v100
	ds_read2_b32 v[100:101], v119 offset1:4
	v_cndmask_b32_e32 v105, v110, v106, vcc
	ds_bpermute_b32 v105, v118, v105
	s_waitcnt lgkmcnt(2)
	v_add_f32_e32 v104, v103, v102
	ds_read2_b32 v[102:103], v119 offset0:8 offset1:12
	s_waitcnt lgkmcnt(2)
	v_add_f32_e32 v100, v100, v104
	v_add_f32_e32 v104, v107, v108
	v_add_f32_e32 v104, v109, v104
	v_add_f32_e32 v104, v110, v104
	s_waitcnt lgkmcnt(1)
	v_add_f32_e32 v104, v104, v105
	v_add_f32_e32 v101, v101, v104
	v_cndmask_b32_e32 v104, v114, v110, vcc
	ds_bpermute_b32 v104, v118, v104
	ds_write2_b32 v119, v100, v101 offset1:4
	v_add_f32_e32 v100, v111, v112
	v_add_f32_e32 v100, v113, v100
	v_cndmask_b32_e32 v101, v0, v114, vcc
	v_add_f32_e32 v100, v114, v100
	ds_bpermute_b32 v101, v118, v101
	s_waitcnt lgkmcnt(2)
	v_add_f32_e32 v100, v100, v104
	v_add_f32_e32 v100, v102, v100
	v_add_f32_e32 v102, v115, v116
	v_add_f32_e32 v102, v117, v102
	v_add_f32_e32 v102, v0, v102
	s_waitcnt lgkmcnt(0)
	v_add_f32_e32 v101, v102, v101
	v_add_f32_e32 v101, v103, v101
	ds_write2_b32 v119, v100, v101 offset0:8 offset1:12
	s_mov_b32 s66, 0x14991000
	s_mov_b32 s67, 0x3f80000
	s_mov_b64 s[68:69], 0x800
	s_movk_i32 s64, 0x1ff0
	s_mov_b32 s65, s91

.LBB0_355:
	v_mov_b32_e32 v66, v169
	v_add_u32_e32 v0, v198, v205
	v_lshlrev_b32_e32 v68, 7, v66
	v_lshrrev_b32_e32 v67, 4, v66
	v_bfe_u32 v98, v66, 4, 2
	v_and_b32_e32 v68, 0x780, v68
	v_and_b32_e32 v66, 7, v66
	v_bitop3_b32 v67, v67, v66, 3 bitop3:0x6c
	v_add_u32_e32 v68, s88, v68
	v_bitop3_b32 v66, v98, v66, 4 bitop3:0x36
	v_lshl_add_u32 v86, v67, 4, v68
	v_lshl_add_u32 v94, v66, 4, v68
	ds_read_b128 v[66:69], v86
	ds_read_b128 v[70:73], v86 offset:2048
	ds_read_b128 v[74:77], v94
	ds_read_b128 v[78:81], v94 offset:2048
	ds_read_b128 v[82:85], v86 offset:4096
	ds_read_b128 v[86:89], v86 offset:6144
	ds_read_b128 v[90:93], v94 offset:4096
	ds_read_b128 v[94:97], v94 offset:6144
	v_cvt_f32_i32_e32 v0, v0
	v_lshlrev_b32_e32 v98, 6, v98
	v_or_b32_e32 v99, 16, v98
	v_cvt_f32_ubyte0_e32 v110, v98
	v_cvt_f32_ubyte0_e32 v111, v99
	v_or_b32_e32 v99, 48, v98
	v_or_b32_e32 v98, 32, v98
	v_pk_add_f32 v[114:115], v[0:1], v[110:111] op_sel_hi:[0,1]
	v_cvt_f32_ubyte0_e32 v113, v99
	v_cvt_f32_ubyte0_e32 v112, v98
	v_pk_add_f32 v[116:117], v[0:1], v[112:113] op_sel_hi:[0,1]
	v_mov_b32_e32 v147, v146
	v_pk_mul_f32 v[98:99], v[156:157], v[114:115]
	v_pk_mul_f32 v[100:101], v[146:147], v[116:117]
	s_waitcnt lgkmcnt(7)
	v_mfma_f32_16x16x32_bf16 v[98:101], v[66:69], v[2:5], v[98:101]
	s_waitcnt lgkmcnt(5)
	v_mfma_f32_16x16x32_bf16 v[98:101], v[74:77], v[6:9], v[98:101]
	v_add_f32_e32 v102, 0x43800000, v0
	v_pk_add_f32 v[118:119], v[102:103], v[110:111] op_sel_hi:[0,1]
	v_pk_add_f32 v[120:121], v[102:103], v[112:113] op_sel_hi:[0,1]
	v_pk_mul_f32 v[104:105], v[146:147], v[120:121]
	v_pk_mul_f32 v[102:103], v[156:157], v[118:119]
	s_nop 0
	v_mfma_f32_16x16x32_bf16 v[102:105], v[70:73], v[2:5], v[102:105]
	s_waitcnt lgkmcnt(4)
	v_mfma_f32_16x16x32_bf16 v[102:105], v[78:81], v[6:9], v[102:105]
	v_add_f32_e32 v106, 0x44000000, v0
	v_pk_add_f32 v[122:123], v[106:107], v[110:111] op_sel_hi:[0,1]
	v_pk_add_f32 v[124:125], v[106:107], v[112:113] op_sel_hi:[0,1]
	v_pk_mul_f32 v[108:109], v[146:147], v[124:125]
	v_pk_mul_f32 v[106:107], v[156:157], v[122:123]
	s_waitcnt lgkmcnt(3)
	v_mfma_f32_16x16x32_bf16 v[106:109], v[82:85], v[2:5], v[106:109]
	s_waitcnt lgkmcnt(1)
	v_mfma_f32_16x16x32_bf16 v[106:109], v[90:93], v[6:9], v[106:109]
	v_add_f32_e32 v0, 0x44400000, v0
	v_pk_add_f32 v[126:127], v[0:1], v[110:111] op_sel_hi:[0,1]
	v_pk_add_f32 v[128:129], v[0:1], v[112:113] op_sel_hi:[0,1]
	v_pk_mul_f32 v[112:113], v[146:147], v[128:129]
	v_pk_mul_f32 v[110:111], v[156:157], v[126:127]
	s_nop 0
	v_mfma_f32_16x16x32_bf16 v[110:113], v[86:89], v[2:5], v[110:113]
	s_waitcnt lgkmcnt(0)
	v_mfma_f32_16x16x32_bf16 v[110:113], v[94:97], v[6:9], v[110:113]
	v_exp_f32_e32 v0, v98
	v_exp_f32_e32 v98, v99
	v_cmp_ge_f32_e32 vcc, 0, v114
	v_cmp_lt_f32_e64 s[0:1], s13, v114
	s_and_b64 vcc, vcc, s[0:1]
	v_cmp_ge_f32_e64 s[0:1], 0, v115
	v_cmp_lt_f32_e64 s[40:41], s13, v115
	v_add_f32_e32 v0, 0, v0
	s_and_b64 s[40:41], s[0:1], s[40:41]
	v_cndmask_b32_e32 v0, 0, v0, vcc
	v_cndmask_b32_e64 v98, 0, v98, s[40:41]
	v_add_f32_e32 v0, v98, v0
	v_exp_f32_e32 v98, v100
	v_cmp_ge_f32_e64 s[0:1], 0, v116
	v_cmp_lt_f32_e64 s[42:43], s13, v116
	s_and_b64 s[42:43], s[0:1], s[42:43]
	v_cmp_ge_f32_e64 s[0:1], 0, v117
	v_cndmask_b32_e64 v98, 0, v98, s[42:43]
	v_add_f32_e32 v0, v98, v0
	v_exp_f32_e32 v98, v101
	v_cmp_lt_f32_e64 s[44:45], s13, v117
	s_and_b64 s[44:45], s[0:1], s[44:45]
	v_cmp_ge_f32_e64 s[0:1], 0, v118
	v_cndmask_b32_e64 v98, 0, v98, s[44:45]
	v_add_f32_e32 v0, v98, v0
	v_exp_f32_e32 v98, v102
	v_cmp_lt_f32_e64 s[46:47], s13, v118
	s_and_b64 s[46:47], s[0:1], s[46:47]
	v_cmp_ge_f32_e64 s[0:1], 0, v119
	v_cndmask_b32_e64 v98, 0, v98, s[46:47]
	v_add_f32_e32 v0, v0, v98
	v_exp_f32_e32 v98, v103
	v_cmp_lt_f32_e64 s[48:49], s13, v119
	s_and_b64 s[48:49], s[0:1], s[48:49]
	v_cmp_ge_f32_e64 s[0:1], 0, v120
	v_cndmask_b32_e64 v98, 0, v98, s[48:49]
	v_add_f32_e32 v0, v98, v0
	v_exp_f32_e32 v98, v104
	v_cmp_lt_f32_e64 s[50:51], s13, v120
	s_and_b64 s[50:51], s[0:1], s[50:51]
	v_cmp_ge_f32_e64 s[0:1], 0, v121
	v_cndmask_b32_e64 v98, 0, v98, s[50:51]
	v_add_f32_e32 v0, v98, v0
	v_exp_f32_e32 v98, v105
	v_cmp_lt_f32_e64 s[52:53], s13, v121
	s_and_b64 s[52:53], s[0:1], s[52:53]
	v_cmp_ge_f32_e64 s[0:1], 0, v122
	v_cndmask_b32_e64 v98, 0, v98, s[52:53]
	v_add_f32_e32 v0, v98, v0
	v_exp_f32_e32 v98, v106
	v_cmp_lt_f32_e64 s[54:55], s13, v122
	s_and_b64 s[54:55], s[0:1], s[54:55]
	v_cmp_ge_f32_e64 s[0:1], 0, v123
	v_cndmask_b32_e64 v98, 0, v98, s[54:55]
	v_add_f32_e32 v0, v0, v98
	v_exp_f32_e32 v98, v107
	v_cmp_lt_f32_e64 s[56:57], s13, v123
	s_and_b64 s[56:57], s[0:1], s[56:57]
	v_cmp_ge_f32_e64 s[0:1], 0, v124
	v_cndmask_b32_e64 v98, 0, v98, s[56:57]
	v_add_f32_e32 v0, v98, v0
	v_exp_f32_e32 v98, v108
	v_cmp_lt_f32_e64 s[58:59], s13, v124
	s_and_b64 s[58:59], s[0:1], s[58:59]
	v_cmp_ge_f32_e64 s[0:1], 0, v125
	v_cndmask_b32_e64 v98, 0, v98, s[58:59]
	v_add_f32_e32 v0, v98, v0
	v_exp_f32_e32 v98, v109
	v_cmp_lt_f32_e64 s[60:61], s13, v125
	s_and_b64 s[60:61], s[0:1], s[60:61]
	v_cmp_ge_f32_e64 s[0:1], 0, v126
	v_cndmask_b32_e64 v98, 0, v98, s[60:61]
	v_add_f32_e32 v0, v98, v0
	v_exp_f32_e32 v98, v110
	v_cmp_lt_f32_e64 s[62:63], s13, v126
	s_and_b64 s[62:63], s[0:1], s[62:63]
	v_cmp_ge_f32_e64 s[0:1], 0, v127
	v_cndmask_b32_e64 v98, 0, v98, s[62:63]
	v_add_f32_e32 v0, v0, v98
	v_exp_f32_e32 v98, v111
	v_cmp_lt_f32_e64 s[64:65], s13, v127
	s_and_b64 s[64:65], s[0:1], s[64:65]
	v_cmp_ge_f32_e64 s[0:1], 0, v128
	v_cndmask_b32_e64 v98, 0, v98, s[64:65]
	v_add_f32_e32 v103, v98, v0
	v_exp_f32_e32 v0, v112
	v_cmp_lt_f32_e64 s[66:67], s13, v128
	s_and_b64 s[68:69], s[0:1], s[66:67]
	v_cmp_ge_f32_e64 s[0:1], 0, v129
	v_cndmask_b32_e64 v105, 0, v0, s[68:69]
	v_exp_f32_e32 v0, v113
	v_cmp_lt_f32_e64 s[66:67], s13, v129
	s_and_b64 s[66:67], s[0:1], s[66:67]
	v_mov_b32_e32 v145, v144
	v_pk_mul_f32 v[98:99], v[158:159], v[114:115]
	v_pk_mul_f32 v[100:101], v[144:145], v[116:117]
	s_nop 0
	v_mfma_f32_16x16x32_bf16 v[66:69], v[66:69], v[10:13], v[98:101]
	v_mfma_f32_16x16x32_bf16 v[66:69], v[74:77], v[14:17], v[66:69]
	v_pk_mul_f32 v[76:77], v[144:145], v[120:121]
	v_pk_mul_f32 v[74:75], v[158:159], v[118:119]
	s_nop 0
	v_mfma_f32_16x16x32_bf16 v[70:73], v[70:73], v[10:13], v[74:77]
	v_mfma_f32_16x16x32_bf16 v[70:73], v[78:81], v[14:17], v[70:73]
	s_nop 0
	v_pk_mul_f32 v[76:77], v[144:145], v[124:125]
	v_pk_mul_f32 v[74:75], v[158:159], v[122:123]
	s_nop 0
	v_mfma_f32_16x16x32_bf16 v[74:77], v[82:85], v[10:13], v[74:77]
	v_mfma_f32_16x16x32_bf16 v[74:77], v[90:93], v[14:17], v[74:77]
	v_pk_mul_f32 v[80:81], v[144:145], v[128:129]
	v_pk_mul_f32 v[78:79], v[158:159], v[126:127]
	s_nop 0
	v_mfma_f32_16x16x32_bf16 v[78:81], v[86:89], v[10:13], v[78:81]
	v_mfma_f32_16x16x32_bf16 v[78:81], v[94:97], v[14:17], v[78:81]
	v_exp_f32_e32 v66, v66
	v_exp_f32_e32 v67, v67
	v_exp_f32_e32 v68, v68
	v_mov_b64_e32 v[98:99], v[160:161]
	v_add_f32_e32 v66, 0, v66
	v_cndmask_b32_e64 v67, 0, v67, s[40:41]
	v_cndmask_b32_e32 v66, 0, v66, vcc
	v_add_f32_e32 v66, v67, v66
	v_exp_f32_e32 v67, v69
	v_cndmask_b32_e64 v68, 0, v68, s[42:43]
	v_add_f32_e32 v66, v68, v66
	v_exp_f32_e32 v68, v70
	v_cndmask_b32_e64 v67, 0, v67, s[44:45]
	v_add_f32_e32 v66, v67, v66
	v_exp_f32_e32 v67, v71
	v_cndmask_b32_e64 v68, 0, v68, s[46:47]
	v_add_f32_e32 v66, v66, v68
	v_exp_f32_e32 v68, v72
	v_cndmask_b32_e64 v67, 0, v67, s[48:49]
	v_add_f32_e32 v66, v67, v66
	v_exp_f32_e32 v67, v73
	v_cndmask_b32_e64 v68, 0, v68, s[50:51]
	v_add_f32_e32 v66, v68, v66
	v_exp_f32_e32 v68, v74
	v_cndmask_b32_e64 v67, 0, v67, s[52:53]
	v_add_f32_e32 v66, v67, v66
	v_exp_f32_e32 v67, v75
	v_cndmask_b32_e64 v68, 0, v68, s[54:55]
	v_add_f32_e32 v66, v66, v68
	v_exp_f32_e32 v68, v76
	v_cndmask_b32_e64 v67, 0, v67, s[56:57]
	v_add_f32_e32 v66, v67, v66
	v_exp_f32_e32 v67, v77
	v_cndmask_b32_e64 v68, 0, v68, s[58:59]
	v_add_f32_e32 v66, v68, v66
	v_exp_f32_e32 v68, v78
	v_cndmask_b32_e64 v67, 0, v67, s[60:61]
	v_add_f32_e32 v66, v67, v66
	v_exp_f32_e32 v67, v79
	v_cndmask_b32_e64 v68, 0, v68, s[62:63]
	v_add_f32_e32 v66, v66, v68
	v_exp_f32_e32 v68, v80
	v_exp_f32_e32 v70, v81
	v_cndmask_b32_e64 v67, 0, v67, s[64:65]
	v_add_f32_e32 v102, v67, v66
	v_cndmask_b32_e64 v104, 0, v68, s[68:69]
	v_pk_add_f32 v[66:67], v[104:105], v[102:103]
	v_cndmask_b32_e64 v69, 0, v0, s[66:67]
	v_cndmask_b32_e64 v68, 0, v70, s[66:67]
	v_pk_add_f32 v[66:67], v[68:69], v[66:67]
	s_mov_b32 s65, s91
	s_movk_i32 s64, 0x1ff0
	s_mov_b64 s[68:69], 0x800
	s_mov_b32 s67, 0x3f80000
	s_mov_b32 s66, 0x14991000
	v_pk_add_f32 v[164:165], v[162:163], v[66:67]
	v_mov_b32_e32 v0, v208
	v_mov_b32_e32 v94, v62
	v_mov_b32_e32 v95, v63
	v_mov_b32_e32 v96, v64
	v_mov_b32_e32 v97, v65
	v_mov_b32_e32 v90, v58
	v_mov_b32_e32 v91, v59
	v_mov_b32_e32 v92, v60
	v_mov_b32_e32 v93, v61
	v_mov_b32_e32 v86, v54
	v_mov_b32_e32 v87, v55
	v_mov_b32_e32 v88, v56
	v_mov_b32_e32 v89, v57
	v_mov_b32_e32 v82, v50
	v_mov_b32_e32 v83, v51
	v_mov_b32_e32 v84, v52
	v_mov_b32_e32 v85, v53
	v_mov_b32_e32 v78, v46
	v_mov_b32_e32 v79, v47
	v_mov_b32_e32 v80, v48
	v_mov_b32_e32 v81, v49
	v_mov_b32_e32 v74, v42
	v_mov_b32_e32 v75, v43
	v_mov_b32_e32 v76, v44
	v_mov_b32_e32 v77, v45
	v_mov_b32_e32 v70, v38
	v_mov_b32_e32 v71, v39
	v_mov_b32_e32 v72, v40
	v_mov_b32_e32 v73, v41
	v_mov_b32_e32 v66, v34
	v_mov_b32_e32 v67, v35
	v_mov_b32_e32 v68, v36
	v_mov_b32_e32 v69, v37

.LBB0_399:
	s_cmp_lt_i32 s39, 32
	s_cselect_b64 vcc, -1, 0
	s_cmp_lt_u32 s39, 64
	s_cselect_b64 s[0:1], -1, 0
	s_cmpk_lt_u32 s39, 0x60
	s_cselect_b64 s[42:43], -1, 0
	v_cndmask_b32_e64 v0, v111, v110, s[42:43]
	v_cndmask_b32_e64 v0, v0, v109, s[0:1]
	v_cndmask_b32_e32 v0, v0, v108, vcc
	s_and_b32 s0, s39, 31
	v_bfe_u32 v0, v0, s0, 1
	v_cmp_eq_u32_e64 s[42:43], 0, v0
	s_cmp_lg_u32 s39, s14
	s_mov_b64 s[0:1], -1
	s_cbranch_scc0 .LBB0_401
	s_lshl_b32 s0, s39, 6
	v_sub_u32_e32 v0, s0, v141
	v_mov_b32_e32 v119, v169
	v_cvt_f32_i32_e32 v99, v0
	v_mov_b32_e32 v101, v100
	v_lshlrev_b32_e32 v0, 7, v119
	v_lshrrev_b32_e32 v133, 4, v119
	v_and_b32_e32 v0, 0x780, v0
	v_and_b32_e32 v138, 7, v119
	v_bfe_u32 v66, v119, 4, 2
	v_bitop3_b32 v67, v133, v138, 3 bitop3:0x6c
	v_add_u32_e32 v139, s38, v0
	v_lshl_add_u32 v0, v67, 4, v139
	v_bitop3_b32 v67, v66, v138, 4 bitop3:0x36
	v_lshl_add_u32 v67, v67, 4, v139
	ds_read_b128 v[70:73], v0
	ds_read_b128 v[74:77], v0 offset:2048
	ds_read_b128 v[78:81], v67
	ds_read_b128 v[86:89], v67 offset:2048
	ds_read_b128 v[90:93], v0 offset:4096
	ds_read_b128 v[94:97], v0 offset:6144
	ds_read_b128 v[120:123], v67 offset:4096
	ds_read_b128 v[124:127], v67 offset:6144
	v_lshlrev_b32_e32 v66, 2, v66
	v_or_b32_e32 v67, 1, v66
	v_cvt_f32_ubyte0_e32 v128, v66
	v_cvt_f32_ubyte0_e32 v129, v67
	v_or_b32_e32 v67, 3, v66
	v_or_b32_e32 v66, 2, v66
	v_cndmask_b32_e64 v0, v99, v193, s[42:43]
	v_cvt_f32_ubyte0_e32 v147, v67
	v_cvt_f32_ubyte0_e32 v146, v66
	v_pk_add_f32 v[150:151], v[0:1], v[128:129] op_sel_hi:[0,1]
	v_pk_add_f32 v[152:153], v[0:1], v[146:147] op_sel_hi:[0,1]
	v_pk_mul_f32 v[68:69], v[100:101], v[152:153]
	v_pk_mul_f32 v[66:67], v[102:103], v[150:151]
	s_waitcnt lgkmcnt(7)
	v_mfma_f32_16x16x32_bf16 v[66:69], v[70:73], v[2:5], v[66:69]
	s_waitcnt lgkmcnt(5)
	v_mfma_f32_16x16x32_bf16 v[66:69], v[78:81], v[6:9], v[66:69]
	v_add_f32_e32 v0, 0x41800000, v99
	v_cndmask_b32_e64 v0, v0, v193, s[42:43]
	v_pk_add_f32 v[154:155], v[0:1], v[128:129] op_sel_hi:[0,1]
	v_pk_add_f32 v[156:157], v[0:1], v[146:147] op_sel_hi:[0,1]
	v_pk_mul_f32 v[84:85], v[100:101], v[156:157]
	v_pk_mul_f32 v[82:83], v[102:103], v[154:155]
	s_nop 0
	v_mfma_f32_16x16x32_bf16 v[82:85], v[74:77], v[2:5], v[82:85]
	s_waitcnt lgkmcnt(4)
	v_mfma_f32_16x16x32_bf16 v[82:85], v[86:89], v[6:9], v[82:85]
	v_add_f32_e32 v0, 0x42000000, v99
	v_cndmask_b32_e64 v0, v0, v193, s[42:43]
	v_pk_add_f32 v[158:159], v[0:1], v[128:129] op_sel_hi:[0,1]
	v_pk_add_f32 v[160:161], v[0:1], v[146:147] op_sel_hi:[0,1]
	v_pk_mul_f32 v[144:145], v[100:101], v[160:161]
	v_pk_mul_f32 v[142:143], v[102:103], v[158:159]
	s_waitcnt lgkmcnt(3)
	v_mfma_f32_16x16x32_bf16 v[142:145], v[90:93], v[2:5], v[142:145]
	s_waitcnt lgkmcnt(1)
	v_mfma_f32_16x16x32_bf16 v[142:145], v[120:123], v[6:9], v[142:145]
	v_add_f32_e32 v0, 0x42400000, v99
	v_cndmask_b32_e64 v0, v0, v193, s[42:43]
	v_pk_add_f32 v[128:129], v[0:1], v[128:129] op_sel_hi:[0,1]
	v_pk_add_f32 v[162:163], v[0:1], v[146:147] op_sel_hi:[0,1]
	v_pk_mul_f32 v[148:149], v[100:101], v[162:163]
	v_pk_mul_f32 v[146:147], v[102:103], v[128:129]
	s_nop 0
	v_mfma_f32_16x16x32_bf16 v[146:149], v[94:97], v[2:5], v[146:149]
	s_waitcnt lgkmcnt(0)
	v_mfma_f32_16x16x32_bf16 v[146:149], v[124:127], v[6:9], v[146:149]
	v_exp_f32_e32 v66, v66
	v_exp_f32_e32 v67, v67
	v_exp_f32_e32 v68, v68
	v_exp_f32_e32 v69, v69
	v_add_f32_e32 v0, 0, v66
	v_exp_f32_e32 v82, v82
	v_add_f32_e32 v0, v67, v0
	v_exp_f32_e32 v83, v83
	v_add_f32_e32 v0, v68, v0
	v_exp_f32_e32 v84, v84
	v_add_f32_e32 v0, v69, v0
	v_exp_f32_e32 v85, v85
	v_add_f32_e32 v0, v0, v82
	v_exp_f32_e32 v99, v142
	v_add_f32_e32 v0, v83, v0
	v_exp_f32_e32 v101, v143
	v_add_f32_e32 v0, v84, v0
	v_exp_f32_e32 v140, v144
	v_add_f32_e32 v0, v85, v0
	v_exp_f32_e32 v142, v145
	v_add_f32_e32 v0, v0, v99
	v_exp_f32_e32 v143, v146
	v_add_f32_e32 v0, v101, v0
	v_exp_f32_e32 v144, v147
	v_add_f32_e32 v0, v140, v0
	v_exp_f32_e32 v145, v148
	v_add_f32_e32 v0, v142, v0
	v_exp_f32_e32 v146, v149
	v_add_f32_e32 v0, v0, v143
	v_add_f32_e32 v0, v144, v0
	v_add_f32_e32 v0, v145, v0
	v_add_f32_e32 v0, v146, v0
	v_cvt_pk_bf16_f32 v66, v66, v67
	v_cvt_pk_bf16_f32 v67, v68, v69
	v_cvt_pk_bf16_f32 v68, v82, v83
	v_cvt_pk_bf16_f32 v69, v84, v85
	v_cvt_pk_bf16_f32 v82, v99, v101
	v_cvt_pk_bf16_f32 v83, v140, v142
	v_cvt_pk_bf16_f32 v84, v143, v144
	v_cvt_pk_bf16_f32 v85, v145, v146
	v_mov_b32_e32 v99, v98
	v_pk_mul_f32 v[144:145], v[98:99], v[152:153]
	v_pk_mul_f32 v[142:143], v[104:105], v[150:151]
	s_nop 0
	v_mfma_f32_16x16x32_bf16 v[70:73], v[70:73], v[10:13], v[142:145]
	v_mfma_f32_16x16x32_bf16 v[70:73], v[78:81], v[14:17], v[70:73]
	v_pk_mul_f32 v[80:81], v[98:99], v[156:157]
	v_pk_mul_f32 v[78:79], v[104:105], v[154:155]
	s_nop 0
	v_mfma_f32_16x16x32_bf16 v[74:77], v[74:77], v[10:13], v[78:81]
	v_mfma_f32_16x16x32_bf16 v[74:77], v[86:89], v[14:17], v[74:77]
	s_nop 0
	v_pk_mul_f32 v[80:81], v[98:99], v[160:161]
	v_pk_mul_f32 v[78:79], v[104:105], v[158:159]
	s_nop 0
	v_mfma_f32_16x16x32_bf16 v[78:81], v[90:93], v[10:13], v[78:81]
	v_mfma_f32_16x16x32_bf16 v[78:81], v[120:123], v[14:17], v[78:81]
	v_pk_mul_f32 v[88:89], v[98:99], v[162:163]
	v_pk_mul_f32 v[86:87], v[104:105], v[128:129]
	s_nop 0
	v_mfma_f32_16x16x32_bf16 v[86:89], v[94:97], v[10:13], v[86:89]
	v_mfma_f32_16x16x32_bf16 v[86:89], v[124:127], v[14:17], v[86:89]
	v_exp_f32_e32 v70, v70
	v_exp_f32_e32 v71, v71
	v_exp_f32_e32 v72, v72
	v_exp_f32_e32 v73, v73
	v_add_f32_e32 v90, 0, v70
	v_exp_f32_e32 v74, v74
	v_add_f32_e32 v90, v71, v90
	v_exp_f32_e32 v75, v75
	v_add_f32_e32 v90, v72, v90
	v_exp_f32_e32 v76, v76
	v_add_f32_e32 v90, v73, v90
	v_exp_f32_e32 v77, v77
	v_add_f32_e32 v90, v90, v74
	v_exp_f32_e32 v78, v78
	v_add_f32_e32 v90, v75, v90
	v_exp_f32_e32 v79, v79
	v_add_f32_e32 v90, v76, v90
	v_exp_f32_e32 v80, v80
	v_add_f32_e32 v90, v77, v90
	v_exp_f32_e32 v81, v81
	v_cvt_pk_bf16_f32 v120, v70, v71
	v_lshrrev_b32_e32 v70, 1, v119
	v_add_f32_e32 v90, v90, v78
	v_exp_f32_e32 v86, v86
	v_cvt_pk_bf16_f32 v123, v76, v77
	v_bfe_u32 v76, v133, 1, 1
	v_and_b32_e32 v70, 8, v70
	v_add_f32_e32 v90, v79, v90
	v_exp_f32_e32 v87, v87
	v_cvt_pk_bf16_f32 v121, v72, v73
	v_cvt_pk_bf16_f32 v122, v74, v75
	v_add_u32_e32 v77, v139, v70
	v_bitop3_b32 v70, v76, v119, 7 bitop3:0x78
	v_bitop3_b32 v72, v76, v138, 2 bitop3:0x36
	v_bitop3_b32 v74, v76, v138, 4 bitop3:0x36
	v_bitop3_b32 v76, v76, v138, 6 bitop3:0x36
	v_add_f32_e32 v90, v80, v90
	v_exp_f32_e32 v88, v88
	v_lshl_add_u32 v101, v70, 4, v77
	v_lshl_add_u32 v119, v72, 4, v77
	v_lshl_add_u32 v128, v74, 4, v77
	v_lshl_add_u32 v129, v76, 4, v77
	v_add_f32_e32 v90, v81, v90
	v_exp_f32_e32 v89, v89
	ds_read_b64 v[70:71], v101 offset:8192
	ds_read_b64 v[72:73], v119 offset:8192
	ds_read_b64 v[74:75], v128 offset:8192
	ds_read_b64 v[76:77], v129 offset:8192
	v_add_f32_e32 v90, v90, v86
	v_add_f32_e32 v90, v87, v90
	v_add_f32_e32 v90, v88, v90
	v_add_f32_e32 v99, v89, v90
	v_cvt_pk_bf16_f32 v124, v78, v79
	v_cvt_pk_bf16_f32 v125, v80, v81
	v_cvt_pk_bf16_f32 v126, v86, v87
	v_cvt_pk_bf16_f32 v127, v88, v89
	s_waitcnt lgkmcnt(2)
	v_mfma_f32_16x16x32_bf16 v[78:81], v[70:73], v[66:69], v[62:65]
	v_mfma_f32_16x16x32_bf16 v[70:73], v[70:73], v[120:123], v[54:57]
	s_waitcnt lgkmcnt(0)
	v_mfma_f32_16x16x32_bf16 v[94:97], v[74:77], v[82:85], v[78:81]
	v_mfma_f32_16x16x32_bf16 v[74:77], v[74:77], v[124:127], v[70:73]
	s_nop 3
	ds_read_b64 v[70:71], v101 offset:10240
	ds_read_b64 v[72:73], v119 offset:10240
	ds_read_b64 v[78:79], v128 offset:10240
	ds_read_b64 v[80:81], v129 offset:10240
	s_waitcnt lgkmcnt(2)
	v_mfma_f32_16x16x32_bf16 v[86:89], v[70:73], v[66:69], v[58:61]
	v_mfma_f32_16x16x32_bf16 v[70:73], v[70:73], v[120:123], v[46:49]
	s_waitcnt lgkmcnt(0)
	v_mfma_f32_16x16x32_bf16 v[90:93], v[78:81], v[82:85], v[86:89]
	v_mfma_f32_16x16x32_bf16 v[78:81], v[78:81], v[124:127], v[70:73]
	s_nop 3
	ds_read_b64 v[70:71], v101 offset:12288
	ds_read_b64 v[72:73], v119 offset:12288
	ds_read_b64 v[142:143], v128 offset:12288
	ds_read_b64 v[144:145], v129 offset:12288
	s_waitcnt lgkmcnt(2)
	v_mfma_f32_16x16x32_bf16 v[86:89], v[70:73], v[66:69], v[50:53]
	v_mfma_f32_16x16x32_bf16 v[70:73], v[70:73], v[120:123], v[38:41]
	s_waitcnt lgkmcnt(0)
	v_mfma_f32_16x16x32_bf16 v[86:89], v[142:145], v[82:85], v[86:89]
	v_mfma_f32_16x16x32_bf16 v[70:73], v[142:145], v[124:127], v[70:73]
	ds_read_b64 v[142:143], v101 offset:14336
	ds_read_b64 v[144:145], v119 offset:14336
	ds_read_b64 v[146:147], v128 offset:14336
	ds_read_b64 v[148:149], v129 offset:14336
	s_waitcnt lgkmcnt(2)
	v_mfma_f32_16x16x32_bf16 v[66:69], v[142:145], v[66:69], v[42:45]
	s_mov_b64 s[0:1], 0
	s_waitcnt lgkmcnt(0)
	v_mfma_f32_16x16x32_bf16 v[82:85], v[146:149], v[82:85], v[66:69]
	v_mfma_f32_16x16x32_bf16 v[66:69], v[142:145], v[120:123], v[34:37]
	v_mfma_f32_16x16x32_bf16 v[66:69], v[146:149], v[124:127], v[66:69]
.LBB0_401:
	s_andn2_b64 vcc, exec, s[0:1]
	s_cbranch_vccnz .LBB0_403
	v_mov_b32_e32 v71, v169
	v_mov_b32_e32 v101, v100
	v_lshlrev_b32_e32 v0, 7, v71
	v_lshrrev_b32_e32 v72, 4, v71
	v_and_b32_e32 v0, 0x780, v0
	v_and_b32_e32 v70, 7, v71
	v_bfe_u32 v66, v71, 4, 2
	v_bitop3_b32 v67, v72, v70, 3 bitop3:0x6c
	v_add_u32_e32 v73, s38, v0
	v_lshl_add_u32 v0, v67, 4, v73
	v_bitop3_b32 v67, v66, v70, 4 bitop3:0x36
	v_lshl_add_u32 v67, v67, 4, v73
	ds_read_b128 v[74:77], v0
	ds_read_b128 v[78:81], v0 offset:2048
	ds_read_b128 v[86:89], v67
	ds_read_b128 v[90:93], v67 offset:2048
	ds_read_b128 v[94:97], v0 offset:4096
	ds_read_b128 v[120:123], v0 offset:6144
	ds_read_b128 v[124:127], v67 offset:4096
	ds_read_b128 v[142:145], v67 offset:6144
	v_lshlrev_b32_e32 v66, 2, v66
	v_or_b32_e32 v67, 1, v66
	v_cvt_f32_ubyte0_e32 v128, v66
	v_cvt_f32_ubyte0_e32 v129, v67
	v_add_f32_e32 v67, v128, v113
	v_cmp_ge_f32_e32 vcc, 0, v67
	v_cmp_lt_f32_e64 s[0:1], s13, v67
	v_or_b32_e32 v67, 3, v66
	v_or_b32_e32 v66, 2, v66
	v_cndmask_b32_e64 v0, v113, v193, s[42:43]
	v_cvt_f32_ubyte0_e32 v157, v67
	v_cvt_f32_ubyte0_e32 v156, v66
	v_pk_add_f32 v[154:155], v[0:1], v[128:129] op_sel_hi:[0,1]
	v_pk_add_f32 v[158:159], v[0:1], v[156:157] op_sel_hi:[0,1]
	v_pk_mul_f32 v[68:69], v[100:101], v[158:159]
	v_pk_mul_f32 v[66:67], v[102:103], v[154:155]
	s_and_b64 s[52:53], vcc, s[0:1]
	s_waitcnt lgkmcnt(7)
	v_mfma_f32_16x16x32_bf16 v[66:69], v[74:77], v[2:5], v[66:69]
	s_waitcnt lgkmcnt(5)
	v_mfma_f32_16x16x32_bf16 v[66:69], v[86:89], v[6:9], v[66:69]
	v_cndmask_b32_e64 v0, v114, v193, s[42:43]
	v_pk_add_f32 v[160:161], v[0:1], v[128:129] op_sel_hi:[0,1]
	v_pk_add_f32 v[162:163], v[0:1], v[156:157] op_sel_hi:[0,1]
	v_pk_mul_f32 v[84:85], v[100:101], v[162:163]
	v_pk_mul_f32 v[82:83], v[102:103], v[160:161]
	s_nop 0
	v_mfma_f32_16x16x32_bf16 v[82:85], v[78:81], v[2:5], v[82:85]
	s_waitcnt lgkmcnt(4)
	v_mfma_f32_16x16x32_bf16 v[82:85], v[90:93], v[6:9], v[82:85]
	v_cndmask_b32_e64 v0, v115, v193, s[42:43]
	v_pk_add_f32 v[164:165], v[0:1], v[128:129] op_sel_hi:[0,1]
	v_pk_add_f32 v[166:167], v[0:1], v[156:157] op_sel_hi:[0,1]
	v_pk_mul_f32 v[148:149], v[100:101], v[166:167]
	v_pk_mul_f32 v[146:147], v[102:103], v[164:165]
	s_waitcnt lgkmcnt(3)
	v_mfma_f32_16x16x32_bf16 v[146:149], v[94:97], v[2:5], v[146:149]
	s_waitcnt lgkmcnt(1)
	v_mfma_f32_16x16x32_bf16 v[146:149], v[124:127], v[6:9], v[146:149]
	v_cndmask_b32_e64 v0, v116, v193, s[42:43]
	v_pk_add_f32 v[174:175], v[0:1], v[128:129] op_sel_hi:[0,1]
	v_pk_add_f32 v[176:177], v[0:1], v[156:157] op_sel_hi:[0,1]
	v_pk_mul_f32 v[152:153], v[100:101], v[176:177]
	v_pk_mul_f32 v[150:151], v[102:103], v[174:175]
	s_nop 0
	v_mfma_f32_16x16x32_bf16 v[150:153], v[120:123], v[2:5], v[150:153]
	s_waitcnt lgkmcnt(0)
	v_mfma_f32_16x16x32_bf16 v[150:153], v[142:145], v[6:9], v[150:153]
	v_exp_f32_e32 v0, v66
	v_exp_f32_e32 v66, v67
	v_add_f32_e32 v67, v129, v113
	v_cmp_ge_f32_e32 vcc, 0, v67
	v_cmp_lt_f32_e64 s[0:1], s13, v67
	v_exp_f32_e32 v67, v68
	v_add_f32_e32 v68, v156, v113
	s_and_b64 s[70:71], vcc, s[0:1]
	v_cmp_ge_f32_e32 vcc, 0, v68
	v_cmp_lt_f32_e64 s[0:1], s13, v68
	v_exp_f32_e32 v68, v69
	v_add_f32_e32 v69, v157, v113
	s_and_b64 s[68:69], vcc, s[0:1]
	v_cmp_ge_f32_e32 vcc, 0, v69
	v_cmp_lt_f32_e64 s[0:1], s13, v69
	v_exp_f32_e32 v69, v82
	v_add_f32_e32 v82, v114, v128
	s_and_b64 s[66:67], vcc, s[0:1]
	v_cmp_ge_f32_e32 vcc, 0, v82
	v_cmp_lt_f32_e64 s[0:1], s13, v82
	v_exp_f32_e32 v82, v83
	v_add_f32_e32 v83, v114, v129
	s_and_b64 s[64:65], vcc, s[0:1]
	v_cmp_ge_f32_e32 vcc, 0, v83
	v_cmp_lt_f32_e64 s[0:1], s13, v83
	v_exp_f32_e32 v83, v84
	v_add_f32_e32 v84, v114, v156
	s_and_b64 s[62:63], vcc, s[0:1]
	v_cmp_ge_f32_e32 vcc, 0, v84
	v_cmp_lt_f32_e64 s[0:1], s13, v84
	v_exp_f32_e32 v84, v85
	v_add_f32_e32 v85, v114, v157
	s_and_b64 s[60:61], vcc, s[0:1]
	v_cmp_ge_f32_e32 vcc, 0, v85
	v_cmp_lt_f32_e64 s[0:1], s13, v85
	v_add_f32_e32 v101, v115, v128
	s_and_b64 s[58:59], vcc, s[0:1]
	v_cmp_ge_f32_e32 vcc, 0, v101
	v_cmp_lt_f32_e64 s[0:1], s13, v101
	v_add_f32_e32 v119, v115, v129
	v_cndmask_b32_e64 v99, 0, v0, s[52:53]
	s_and_b64 s[56:57], vcc, s[0:1]
	v_cmp_ge_f32_e32 vcc, 0, v119
	v_cmp_lt_f32_e64 s[0:1], s13, v119
	v_add_f32_e32 v133, v115, v156
	v_add_f32_e32 v0, 0, v99
	v_cndmask_b32_e64 v66, 0, v66, s[70:71]
	s_and_b64 s[54:55], vcc, s[0:1]
	v_cmp_ge_f32_e32 vcc, 0, v133
	v_cmp_lt_f32_e64 s[0:1], s13, v133
	v_add_f32_e32 v138, v115, v157
	v_add_f32_e32 v0, v66, v0
	v_cndmask_b32_e64 v67, 0, v67, s[68:69]
	s_and_b64 s[50:51], vcc, s[0:1]
	v_cmp_ge_f32_e32 vcc, 0, v138
	v_cmp_lt_f32_e64 s[0:1], s13, v138
	v_exp_f32_e32 v138, v150
	v_add_f32_e32 v0, v67, v0
	v_cndmask_b32_e64 v68, 0, v68, s[66:67]
	v_add_f32_e32 v128, v116, v128
	v_add_f32_e32 v0, v68, v0
	v_cndmask_b32_e64 v69, 0, v69, s[64:65]
	v_exp_f32_e32 v85, v146
	s_and_b64 s[48:49], vcc, s[0:1]
	v_cmp_ge_f32_e32 vcc, 0, v128
	v_cmp_lt_f32_e64 s[0:1], s13, v128
	v_add_f32_e32 v0, v0, v69
	v_cndmask_b32_e64 v82, 0, v82, s[62:63]
	v_exp_f32_e32 v101, v147
	s_and_b64 s[46:47], vcc, s[0:1]
	v_add_f32_e32 v0, v82, v0
	v_cndmask_b32_e64 v83, 0, v83, s[60:61]
	v_exp_f32_e32 v119, v148
	v_cndmask_b32_e64 v128, 0, v138, s[46:47]
	v_exp_f32_e32 v138, v151
	v_add_f32_e32 v0, v83, v0
	v_cndmask_b32_e64 v84, 0, v84, s[58:59]
	v_exp_f32_e32 v133, v149
	v_add_f32_e32 v129, v116, v129
	v_add_f32_e32 v0, v84, v0
	v_cndmask_b32_e64 v85, 0, v85, s[56:57]
	v_cmp_ge_f32_e32 vcc, 0, v129
	v_cmp_lt_f32_e64 s[0:1], s13, v129
	v_add_f32_e32 v0, v0, v85
	v_cndmask_b32_e64 v101, 0, v101, s[54:55]
	s_and_b64 s[44:45], vcc, s[0:1]
	v_add_f32_e32 v0, v101, v0
	v_cndmask_b32_e64 v119, 0, v119, s[50:51]
	v_cndmask_b32_e64 v129, 0, v138, s[44:45]
	v_exp_f32_e32 v138, v152
	v_add_f32_e32 v139, v116, v156
	v_add_f32_e32 v0, v119, v0
	v_cndmask_b32_e64 v133, 0, v133, s[48:49]
	v_cmp_ge_f32_e32 vcc, 0, v139
	v_cmp_lt_f32_e64 s[0:1], s13, v139
	v_exp_f32_e32 v139, v153
	v_add_f32_e32 v0, v133, v0
	v_add_f32_e32 v140, v116, v157
	v_add_f32_e32 v0, v0, v128
	s_and_b64 s[42:43], vcc, s[0:1]
	v_cmp_ge_f32_e32 vcc, 0, v140
	v_cmp_lt_f32_e64 s[0:1], s13, v140
	v_add_f32_e32 v0, v129, v0
	v_cndmask_b32_e64 v138, 0, v138, s[42:43]
	s_and_b64 vcc, vcc, s[0:1]
	v_add_f32_e32 v0, v138, v0
	v_cndmask_b32_e32 v139, 0, v139, vcc
	v_add_f32_e32 v0, v139, v0
	v_cvt_pk_bf16_f32 v66, v99, v66
	v_cvt_pk_bf16_f32 v67, v67, v68
	v_cvt_pk_bf16_f32 v68, v69, v82
	v_cvt_pk_bf16_f32 v69, v83, v84
	v_cvt_pk_bf16_f32 v82, v85, v101
	v_cvt_pk_bf16_f32 v83, v119, v133
	v_cvt_pk_bf16_f32 v84, v128, v129
	v_cvt_pk_bf16_f32 v85, v138, v139
	v_mov_b32_e32 v99, v98
	v_pk_mul_f32 v[148:149], v[98:99], v[158:159]
	v_pk_mul_f32 v[146:147], v[104:105], v[154:155]
	s_nop 0
	v_mfma_f32_16x16x32_bf16 v[74:77], v[74:77], v[10:13], v[146:149]
	v_mfma_f32_16x16x32_bf16 v[74:77], v[86:89], v[14:17], v[74:77]
	v_pk_mul_f32 v[88:89], v[98:99], v[162:163]
	v_pk_mul_f32 v[86:87], v[104:105], v[160:161]
	s_nop 0
	v_mfma_f32_16x16x32_bf16 v[78:81], v[78:81], v[10:13], v[86:89]
	v_mfma_f32_16x16x32_bf16 v[78:81], v[90:93], v[14:17], v[78:81]
	s_nop 0
	v_pk_mul_f32 v[88:89], v[98:99], v[166:167]
	v_pk_mul_f32 v[86:87], v[104:105], v[164:165]
	s_nop 0
	v_mfma_f32_16x16x32_bf16 v[86:89], v[94:97], v[10:13], v[86:89]
	v_mfma_f32_16x16x32_bf16 v[86:89], v[124:127], v[14:17], v[86:89]
	v_pk_mul_f32 v[92:93], v[98:99], v[176:177]
	v_pk_mul_f32 v[90:91], v[104:105], v[174:175]
	s_nop 0
	v_mfma_f32_16x16x32_bf16 v[90:93], v[120:123], v[10:13], v[90:93]
	v_mfma_f32_16x16x32_bf16 v[90:93], v[142:145], v[14:17], v[90:93]
	v_exp_f32_e32 v74, v74
	v_exp_f32_e32 v75, v75
	v_exp_f32_e32 v76, v76
	v_exp_f32_e32 v77, v77
	v_cndmask_b32_e64 v74, 0, v74, s[52:53]
	v_exp_f32_e32 v78, v78
	v_add_f32_e32 v94, 0, v74
	v_cndmask_b32_e64 v75, 0, v75, s[70:71]
	v_exp_f32_e32 v79, v79
	v_add_f32_e32 v94, v75, v94
	v_cndmask_b32_e64 v76, 0, v76, s[68:69]
	v_exp_f32_e32 v80, v80
	v_add_f32_e32 v94, v76, v94
	v_cndmask_b32_e64 v77, 0, v77, s[66:67]
	v_exp_f32_e32 v81, v81
	v_add_f32_e32 v94, v77, v94
	v_cndmask_b32_e64 v78, 0, v78, s[64:65]
	v_exp_f32_e32 v86, v86
	v_add_f32_e32 v94, v94, v78
	v_cndmask_b32_e64 v79, 0, v79, s[62:63]
	v_exp_f32_e32 v87, v87
	v_add_f32_e32 v94, v79, v94
	v_cndmask_b32_e64 v80, 0, v80, s[60:61]
	v_exp_f32_e32 v88, v88
	v_cvt_pk_bf16_f32 v122, v78, v79
	v_bfe_u32 v78, v72, 1, 1
	v_lshrrev_b32_e32 v72, 1, v71
	v_add_f32_e32 v94, v80, v94
	v_cndmask_b32_e64 v81, 0, v81, s[58:59]
	v_exp_f32_e32 v89, v89
	v_and_b32_e32 v72, 8, v72
	v_add_f32_e32 v94, v81, v94
	v_cndmask_b32_e64 v86, 0, v86, s[56:57]
	v_exp_f32_e32 v90, v90
	v_add_u32_e32 v79, v73, v72
	v_bitop3_b32 v71, v78, v71, 7 bitop3:0x78
	v_add_f32_e32 v94, v94, v86
	v_cndmask_b32_e64 v87, 0, v87, s[54:55]
	v_exp_f32_e32 v91, v91
	v_lshl_add_u32 v101, v71, 4, v79
	v_bitop3_b32 v71, v78, v70, 2 bitop3:0x36
	v_add_f32_e32 v94, v87, v94
	v_cndmask_b32_e64 v88, 0, v88, s[50:51]
	v_exp_f32_e32 v92, v92
	v_lshl_add_u32 v119, v71, 4, v79
	v_bitop3_b32 v71, v78, v70, 4 bitop3:0x36
	v_bitop3_b32 v70, v78, v70, 6 bitop3:0x36
	v_add_f32_e32 v94, v88, v94
	v_cndmask_b32_e64 v89, 0, v89, s[48:49]
	v_exp_f32_e32 v93, v93
	v_lshl_add_u32 v128, v71, 4, v79
	v_lshl_add_u32 v129, v70, 4, v79
	v_add_f32_e32 v94, v89, v94
	v_cndmask_b32_e64 v90, 0, v90, s[46:47]
	v_cvt_pk_bf16_f32 v120, v74, v75
	v_cvt_pk_bf16_f32 v121, v76, v77
	ds_read_b64 v[72:73], v101 offset:8192
	ds_read_b64 v[74:75], v119 offset:8192
	ds_read_b64 v[76:77], v128 offset:8192
	ds_read_b64 v[78:79], v129 offset:8192
	v_add_f32_e32 v94, v94, v90
	v_cndmask_b32_e64 v91, 0, v91, s[44:45]
	v_add_f32_e32 v94, v91, v94
	v_cndmask_b32_e64 v92, 0, v92, s[42:43]
	v_add_f32_e32 v94, v92, v94
	v_cndmask_b32_e32 v93, 0, v93, vcc
	s_mov_b64 s[70:71], 0x100
	s_mov_b64 s[68:69], 0x800
	s_mov_b32 s67, 0x3f80000
	s_mov_b32 s66, 0x14991000
	s_mov_b32 s65, s91
	s_movk_i32 s64, 0x1ff0
	v_add_f32_e32 v99, v93, v94
	v_cvt_pk_bf16_f32 v123, v80, v81
	v_cvt_pk_bf16_f32 v124, v86, v87
	v_cvt_pk_bf16_f32 v125, v88, v89
	v_cvt_pk_bf16_f32 v126, v90, v91
	v_cvt_pk_bf16_f32 v127, v92, v93
	s_waitcnt lgkmcnt(2)
	v_mfma_f32_16x16x32_bf16 v[62:65], v[72:75], v[66:69], v[62:65]
	v_mfma_f32_16x16x32_bf16 v[54:57], v[72:75], v[120:123], v[54:57]
	s_waitcnt lgkmcnt(0)
	v_mfma_f32_16x16x32_bf16 v[94:97], v[76:79], v[82:85], v[62:65]
	v_mfma_f32_16x16x32_bf16 v[74:77], v[76:79], v[124:127], v[54:57]
	s_nop 3
	ds_read_b64 v[54:55], v101 offset:10240
	ds_read_b64 v[56:57], v119 offset:10240
	ds_read_b64 v[62:63], v128 offset:10240
	ds_read_b64 v[64:65], v129 offset:10240
	s_waitcnt lgkmcnt(2)
	v_mfma_f32_16x16x32_bf16 v[58:61], v[54:57], v[66:69], v[58:61]
	v_mfma_f32_16x16x32_bf16 v[46:49], v[54:57], v[120:123], v[46:49]
	s_waitcnt lgkmcnt(0)
	v_mfma_f32_16x16x32_bf16 v[90:93], v[62:65], v[82:85], v[58:61]
	v_mfma_f32_16x16x32_bf16 v[78:81], v[62:65], v[124:127], v[46:49]
	s_nop 3
	ds_read_b64 v[46:47], v101 offset:12288
	ds_read_b64 v[48:49], v119 offset:12288
	ds_read_b64 v[54:55], v128 offset:12288
	ds_read_b64 v[56:57], v129 offset:12288
	s_waitcnt lgkmcnt(2)
	v_mfma_f32_16x16x32_bf16 v[50:53], v[46:49], v[66:69], v[50:53]
	v_mfma_f32_16x16x32_bf16 v[38:41], v[46:49], v[120:123], v[38:41]
	s_waitcnt lgkmcnt(0)
	v_mfma_f32_16x16x32_bf16 v[86:89], v[54:57], v[82:85], v[50:53]
	v_mfma_f32_16x16x32_bf16 v[70:73], v[54:57], v[124:127], v[38:41]
	s_nop 3
	ds_read_b64 v[38:39], v101 offset:14336
	ds_read_b64 v[40:41], v119 offset:14336
	ds_read_b64 v[46:47], v128 offset:14336
	ds_read_b64 v[48:49], v129 offset:14336
	s_waitcnt lgkmcnt(2)
	v_mfma_f32_16x16x32_bf16 v[42:45], v[38:41], v[66:69], v[42:45]
	v_mfma_f32_16x16x32_bf16 v[34:37], v[38:41], v[120:123], v[34:37]
	s_waitcnt lgkmcnt(0)
	v_mfma_f32_16x16x32_bf16 v[82:85], v[46:49], v[82:85], v[42:45]
	v_mfma_f32_16x16x32_bf16 v[66:69], v[46:49], v[124:127], v[34:37]
.LBB0_403:
	v_add_f32_e32 v118, v118, v0
	v_add_f32_e32 v117, v117, v99
	s_add_i32 s31, s31, 4
	s_addk_i32 s36, 0x4000
	s_and_b64 vcc, exec, s[34:35]
	s_cbranch_vccnz .LBB0_389
	s_nop 0
	v_mov_b32_e32 v34, v66
	v_mov_b32_e32 v35, v67
	v_mov_b32_e32 v36, v68
	v_mov_b32_e32 v37, v69
	v_mov_b32_e32 v38, v70
	v_mov_b32_e32 v39, v71
	v_mov_b32_e32 v40, v72
	v_mov_b32_e32 v41, v73
	v_mov_b32_e32 v46, v78
	v_mov_b32_e32 v47, v79
	v_mov_b32_e32 v48, v80
	v_mov_b32_e32 v49, v81
	v_mov_b32_e32 v54, v74
	v_mov_b32_e32 v55, v75
	v_mov_b32_e32 v56, v76
	v_mov_b32_e32 v57, v77
	v_mov_b32_e32 v42, v82
	v_mov_b32_e32 v43, v83
	v_mov_b32_e32 v44, v84
	v_mov_b32_e32 v45, v85
	v_mov_b32_e32 v50, v86
	v_mov_b32_e32 v51, v87
	v_mov_b32_e32 v52, v88
	v_mov_b32_e32 v53, v89
	v_mov_b32_e32 v58, v90
	v_mov_b32_e32 v59, v91
	v_mov_b32_e32 v60, v92
	v_mov_b32_e32 v61, v93
	v_mov_b32_e32 v62, v94
	v_mov_b32_e32 v63, v95
	v_mov_b32_e32 v64, v96
	v_mov_b32_e32 v65, v97
	s_branch .LBB0_397
